# gate-GEMM epilogue ln_w/ln_b quads loaded once per tile; FoX norm-maxima loop issues its 32 row loads in two batches
# speedup vs baseline: 1.0074x; 1.0032x over previous
;     ...
;     const bf16_t* ap = A + (size_t)(m0 + lrow) * lda + lsw;
;     const bf16_t* bp = Wt + (size_t)(n0 + lrow) * K + lsw;
;     const size_t a32 = (size_t)32 * lda, b32 = (size_t)32 * K;
;     typedef __attribute__((address_space(3))) unsigned lds_u32;
;     lds_u32* sbase = (lds_u32*)(smem) + wave * 256;
;     ...
;     GLDS(ap, 0, 0, 0)
;     asm volatile("s_waitcnt vmcnt(0)" ::: "memory");
;     __syncthreads();
;     for (int kt = 0; kt < KT; kt++) {
;       const int cur = (kt & 1) * 16384;
;       if (kt + 1 < KT) {
;         const bf16_t* apx = ap;
;         int kc = (kt + 1) * 64;
;         if (SHIFT && kc >= 1024) { apx = ap - lda; kc -= 1024; }
;         const int nxt = ((kt + 1) & 1) * 16384;
;         GLDS(apx, kc, (kt + 1) * 64, nxt)
;       }
; #pragma unroll
;       for (int kk = 0; kk < 2; kk++) {
;         bf16x8 af[4], bfr[4];
;         const int csw = (((kk * 4 + fq) ^ fsw) << 3);
; #pragma unroll
;         for (int mi = 0; mi < 4; mi++) af[mi] = *(const bf16x8*)(smem + cur + (wm * 64 + mi * 16 + fr) * 64 + csw);
; #pragma unroll
;         for (int ni = 0; ni < 4; ni++) bfr[ni] = *(const bf16x8*)(smem + cur + 8192 + (wn * 64 + ni * 16 + fr) * 64 + csw);
; #pragma unroll
;         for (int mi = 0; mi < 4; mi++)
; #pragma unroll
;           for (int ni = 0; ni < 4; ni++)
;             acc[mi][ni] = TR ? __builtin_amdgcn_mfma_f32_16x16x32_bf16(bfr[ni], af[mi], acc[mi][ni], 0, 0, 0)
;                              : __builtin_amdgcn_mfma_f32_16x16x32_bf16(af[mi], bfr[ni], acc[mi][ni], 0, 0, 0);
;       }
;       asm volatile("s_waitcnt vmcnt(0)" ::: "memory");
;       __syncthreads();
.LBB0_445:
	s_lshl_b32 s0, s9, 7
	s_lshl_b32 s1, s8, 7
	v_add_u32_e32 v8, s0, v115
	v_mad_i64_i32 v[76:77], s[8:9], v8, s45, v[78:79]
	v_add_u32_e32 v8, s1, v115
	s_movk_i32 s5, 0x180
	v_mad_i64_i32 v[10:11], s[8:9], v8, s5, v[80:81]
	v_readfirstlane_b32 s5, v123
	s_mov_b64 s[8:9], 0x5000
	v_add_u32_e32 v8, 0x1000, v123
	s_mov_b32 m0, s5
	v_lshl_add_u64 v[12:13], v[76:77], 0, s[8:9]
	v_readfirstlane_b32 s8, v8
	v_add_u32_e32 v8, 0x2000, v123
	global_load_lds_dwordx4 v[76:77], off
	s_mov_b32 m0, s8
	s_mov_b64 s[10:11], 0xa000
	v_readfirstlane_b32 s9, v8
	global_load_lds_dwordx4 v[12:13], off
	v_lshl_add_u64 v[12:13], v[76:77], 0, s[10:11]
	s_mov_b32 m0, s9
	s_mov_b64 s[10:11], 0xf000
	v_add_u32_e32 v8, 0x3000, v123
	global_load_lds_dwordx4 v[12:13], off
	v_lshl_add_u64 v[12:13], v[76:77], 0, s[10:11]
	v_readfirstlane_b32 s10, v8
	v_add_u32_e32 v8, 0x4000, v123
	s_mov_b32 m0, s10
	v_readfirstlane_b32 s11, v8
	s_mov_b64 s[12:13], 0x3000
	v_add_u32_e32 v8, 0x5000, v123
	global_load_lds_dwordx4 v[12:13], off
	s_mov_b32 m0, s11
	v_lshl_add_u64 v[12:13], v[10:11], 0, s[12:13]
	v_readfirstlane_b32 s12, v8
	v_add_u32_e32 v8, 0x6000, v123
	global_load_lds_dwordx4 v[10:11], off
	s_mov_b32 m0, s12
	s_mov_b64 s[14:15], 0x6000
	v_readfirstlane_b32 s13, v8
	global_load_lds_dwordx4 v[12:13], off
	v_lshl_add_u64 v[12:13], v[10:11], 0, s[14:15]
	s_mov_b32 m0, s13
	s_mov_b64 s[14:15], 0x9000
	v_add_u32_e32 v8, 0x7000, v123
	global_load_lds_dwordx4 v[12:13], off
	v_lshl_add_u64 v[12:13], v[10:11], 0, s[14:15]
	v_readfirstlane_b32 s14, v8
	v_add_u32_e32 v8, 0x8000, v123
	s_mov_b32 m0, s14
	s_mov_b64 s[18:19], 0x80
	v_readfirstlane_b32 s15, v8
	v_add_u32_e32 v8, 0x9000, v123
	global_load_lds_dwordx4 v[12:13], off
	v_lshl_add_u64 v[12:13], v[76:77], 0, s[18:19]
	s_mov_b32 m0, s15
	s_mov_b64 s[16:17], 0x5080
	v_readfirstlane_b32 s15, v8
	v_add_u32_e32 v8, 0xa000, v123
	s_waitcnt vmcnt(0)
	s_waitcnt vmcnt(0) lgkmcnt(0)
	s_barrier
	global_load_lds_dwordx4 v[12:13], off
	v_lshl_add_u64 v[12:13], v[76:77], 0, s[16:17]
	s_mov_b32 m0, s15
	s_mov_b64 s[16:17], 0xa080
	v_readfirstlane_b32 s15, v8
	v_add_u32_e32 v8, 0xb000, v123
	global_load_lds_dwordx4 v[12:13], off
	v_lshl_add_u64 v[12:13], v[76:77], 0, s[16:17]
	s_mov_b32 m0, s15
	s_mov_b64 s[16:17], 0xf080
	v_readfirstlane_b32 s15, v8
	v_add_u32_e32 v8, 0xc000, v123
	global_load_lds_dwordx4 v[12:13], off
	v_lshl_add_u64 v[12:13], v[76:77], 0, s[16:17]
	s_mov_b32 m0, s15
	v_readfirstlane_b32 s15, v8
	v_add_u32_e32 v8, 0xd000, v123
	global_load_lds_dwordx4 v[12:13], off
	v_lshl_add_u64 v[12:13], v[10:11], 0, s[18:19]
	s_mov_b32 m0, s15
	s_mov_b64 s[16:17], 0x3080
	v_readfirstlane_b32 s15, v8
	v_add_u32_e32 v8, 0xe000, v123
	global_load_lds_dwordx4 v[12:13], off
	v_lshl_add_u64 v[12:13], v[10:11], 0, s[16:17]
	s_mov_b32 m0, s15
	s_mov_b64 s[16:17], 0x6080
	v_readfirstlane_b32 s15, v8
	v_add_u32_e32 v8, 0xf000, v123
	global_load_lds_dwordx4 v[12:13], off
	v_lshl_add_u64 v[12:13], v[10:11], 0, s[16:17]
	s_mov_b32 m0, s15
	s_mov_b64 s[16:17], 0x9080
	v_readfirstlane_b32 s15, v8
	global_load_lds_dwordx4 v[12:13], off
	v_lshl_add_u64 v[12:13], v[10:11], 0, s[16:17]
	s_mov_b32 m0, s15
	s_mov_b64 s[18:19], 0x100
	global_load_lds_dwordx4 v[12:13], off
	ds_read_b128 v[12:15], v127
	ds_read_b128 v[16:19], v127 offset:2048
	ds_read_b128 v[20:23], v127 offset:4096
	ds_read_b128 v[24:27], v127 offset:6144
	ds_read_b128 v[28:31], v128 offset:16384
	ds_read_b128 v[32:35], v128 offset:18432
	ds_read_b128 v[36:39], v128 offset:20480
	ds_read_b128 v[40:43], v128 offset:22528
	s_waitcnt lgkmcnt(0)
	v_mfma_f32_16x16x32_bf16 v[44:47], v[28:31], v[12:15], 0
	s_mov_b32 m0, s5
	s_mov_b64 s[16:17], 0x5100
	v_add_u32_e32 v8, s0, v124
	v_mfma_f32_16x16x32_bf16 v[48:51], v[32:35], v[12:15], 0
	s_mov_b32 s24, 0xfc0fc0fd
	s_movk_i32 s0, 0x4100
	v_cmp_gt_u32_e32 vcc, s0, v8
	v_mfma_f32_16x16x32_bf16 v[52:55], v[36:39], v[12:15], 0
	s_mov_b32 s5, 0x800000
	v_mfma_f32_16x16x32_bf16 v[12:15], v[40:43], v[12:15], 0
	v_mfma_f32_16x16x32_bf16 v[56:59], v[28:31], v[16:19], 0
	v_mfma_f32_16x16x32_bf16 v[60:63], v[32:35], v[16:19], 0
	v_mfma_f32_16x16x32_bf16 v[64:67], v[36:39], v[16:19], 0
	v_mfma_f32_16x16x32_bf16 v[16:19], v[40:43], v[16:19], 0
	v_mfma_f32_16x16x32_bf16 v[68:71], v[28:31], v[20:23], 0
	v_mfma_f32_16x16x32_bf16 v[72:75], v[32:35], v[20:23], 0
	v_mfma_f32_16x16x32_bf16 v[82:85], v[36:39], v[20:23], 0
	v_mfma_f32_16x16x32_bf16 v[20:23], v[40:43], v[20:23], 0
	v_mfma_f32_16x16x32_bf16 v[28:31], v[28:31], v[24:27], 0
	v_mfma_f32_16x16x32_bf16 v[32:35], v[32:35], v[24:27], 0
	v_mfma_f32_16x16x32_bf16 v[36:39], v[36:39], v[24:27], 0
	v_mfma_f32_16x16x32_bf16 v[24:27], v[40:43], v[24:27], 0
	ds_read_b128 v[40:43], v129
	ds_read_b128 v[86:89], v129 offset:2048
	ds_read_b128 v[90:93], v129 offset:4096
	ds_read_b128 v[94:97], v129 offset:6144
	ds_read_b128 v[98:101], v130 offset:16384
	ds_read_b128 v[102:105], v130 offset:18432
	ds_read_b128 v[106:109], v130 offset:20480
	ds_read_b128 v[110:113], v130 offset:22528
	s_waitcnt vmcnt(0)
	s_waitcnt vmcnt(0) lgkmcnt(0)
	v_mfma_f32_16x16x32_bf16 v[44:47], v[98:101], v[40:43], v[44:47]
	s_barrier
;     ...
;     for (int kt = 0; kt < KT; kt++) {
;       const int cur = (kt & 1) * 16384;
;       if (kt + 1 < KT) {
;         const bf16_t* apx = ap;
;         int kc = (kt + 1) * 64;
;         if (SHIFT && kc >= 1024) { apx = ap - lda; kc -= 1024; }
;         const int nxt = ((kt + 1) & 1) * 16384;
;         GLDS(apx, kc, (kt + 1) * 64, nxt)
;       }
; #pragma unroll
;       for (int kk = 0; kk < 2; kk++) {
;         bf16x8 af[4], bfr[4];
;         const int csw = (((kk * 4 + fq) ^ fsw) << 3);
; #pragma unroll
;         for (int mi = 0; mi < 4; mi++) af[mi] = *(const bf16x8*)(smem + cur + (wm * 64 + mi * 16 + fr) * 64 + csw);
; #pragma unroll
;         for (int ni = 0; ni < 4; ni++) bfr[ni] = *(const bf16x8*)(smem + cur + 8192 + (wn * 64 + ni * 16 + fr) * 64 + csw);
; #pragma unroll
;         for (int mi = 0; mi < 4; mi++)
; #pragma unroll
;           for (int ni = 0; ni < 4; ni++)
;             acc[mi][ni] = TR ? __builtin_amdgcn_mfma_f32_16x16x32_bf16(bfr[ni], af[mi], acc[mi][ni], 0, 0, 0)
;                              : __builtin_amdgcn_mfma_f32_16x16x32_bf16(af[mi], bfr[ni], acc[mi][ni], 0, 0, 0);
;       }
;       asm volatile("s_waitcnt vmcnt(0)" ::: "memory");
;       __syncthreads();
;     }
	v_mfma_f32_16x16x32_bf16 v[48:51], v[102:105], v[40:43], v[48:51]
	v_mfma_f32_16x16x32_bf16 v[52:55], v[106:109], v[40:43], v[52:55]
	v_mfma_f32_16x16x32_bf16 v[12:15], v[110:113], v[40:43], v[12:15]
	v_mfma_f32_16x16x32_bf16 v[40:43], v[98:101], v[86:89], v[56:59]
	v_mfma_f32_16x16x32_bf16 v[56:59], v[102:105], v[86:89], v[60:63]
	v_mfma_f32_16x16x32_bf16 v[60:63], v[106:109], v[86:89], v[64:67]
	v_mfma_f32_16x16x32_bf16 v[64:67], v[98:101], v[90:93], v[68:71]
	v_mfma_f32_16x16x32_bf16 v[68:71], v[102:105], v[90:93], v[72:75]
	v_mfma_f32_16x16x32_bf16 v[72:75], v[106:109], v[90:93], v[82:85]
	s_nop 2
	v_lshl_add_u64 v[82:83], v[76:77], 0, s[18:19]
	global_load_lds_dwordx4 v[82:83], off
	v_lshl_add_u64 v[82:83], v[76:77], 0, s[16:17]
	s_mov_b32 m0, s8
	s_mov_b64 s[16:17], 0xa100
	global_load_lds_dwordx4 v[82:83], off
	v_lshl_add_u64 v[82:83], v[76:77], 0, s[16:17]
	s_mov_b32 m0, s9
	s_mov_b64 s[8:9], 0xf100
	global_load_lds_dwordx4 v[82:83], off
	v_lshl_add_u64 v[76:77], v[76:77], 0, s[8:9]
	s_mov_b32 m0, s10
	s_mov_b64 s[8:9], 0x3100
	global_load_lds_dwordx4 v[76:77], off
	v_lshl_add_u64 v[76:77], v[10:11], 0, s[18:19]
	s_mov_b32 m0, s11
	v_mfma_f32_16x16x32_bf16 v[16:19], v[110:113], v[86:89], v[16:19]
	global_load_lds_dwordx4 v[76:77], off
	v_lshl_add_u64 v[76:77], v[10:11], 0, s[8:9]
	s_mov_b32 m0, s12
	s_mov_b64 s[8:9], 0x6100
	global_load_lds_dwordx4 v[76:77], off
	v_lshl_add_u64 v[76:77], v[10:11], 0, s[8:9]
	s_mov_b32 m0, s13
	s_mov_b64 s[8:9], 0x9100
	global_load_lds_dwordx4 v[76:77], off
	v_lshl_add_u64 v[10:11], v[10:11], 0, s[8:9]
	s_mov_b32 m0, s14
	v_mfma_f32_16x16x32_bf16 v[20:23], v[110:113], v[90:93], v[20:23]
	global_load_lds_dwordx4 v[10:11], off
	v_readlane_b32 s8, v247, 7
	v_mfma_f32_16x16x32_bf16 v[28:31], v[98:101], v[94:97], v[28:31]
	v_readlane_b32 s15, v247, 14
	s_movk_i32 s15, 0xc00
	v_readlane_b32 s10, v247, 9
	v_mfma_f32_16x16x32_bf16 v[32:35], v[102:105], v[94:97], v[32:35]
	v_readlane_b32 s11, v247, 10
	v_readlane_b32 s10, v246, 9
	v_readlane_b32 s11, v246, 10
	v_mfma_f32_16x16x32_bf16 v[36:39], v[106:109], v[94:97], v[36:39]
	v_readlane_b32 s12, v247, 11
	v_readlane_b32 s13, v247, 12
	v_readlane_b32 s12, v246, 11
	v_mfma_f32_16x16x32_bf16 v[24:27], v[110:113], v[94:97], v[24:27]
	ds_read_b128 v[82:85], v127 offset:32768
	ds_read_b128 v[86:89], v127 offset:34816
	ds_read_b128 v[90:93], v127 offset:36864
	ds_read_b128 v[94:97], v127 offset:38912
	ds_read_b128 v[98:101], v128 offset:49152
	ds_read_b128 v[102:105], v128 offset:51200
	ds_read_b128 v[106:109], v128 offset:53248
	ds_read_b128 v[110:113], v128 offset:55296
	v_readlane_b32 s14, v247, 13
	v_readlane_b32 s16, v247, 15
	s_waitcnt lgkmcnt(0)
	v_mfma_f32_16x16x32_bf16 v[44:47], v[98:101], v[82:85], v[44:47]
	v_readlane_b32 s17, v247, 16
	v_readlane_b32 s13, v246, 12
	v_readlane_b32 s18, v247, 17
	v_mfma_f32_16x16x32_bf16 v[48:51], v[102:105], v[82:85], v[48:51]
	v_readlane_b32 s19, v247, 18
	s_movk_i32 s14, 0x70
	v_readlane_b32 s9, v247, 8
	v_mfma_f32_16x16x32_bf16 v[52:55], v[106:109], v[82:85], v[52:55]
	v_readlane_b32 s8, v247, 25
	v_readlane_b32 s9, v247, 26
	v_readlane_b32 s20, v247, 19
	v_mfma_f32_16x16x32_bf16 v[10:13], v[110:113], v[82:85], v[12:15]
	v_readlane_b32 s21, v247, 20
	v_readlane_b32 s22, v247, 21
	v_readlane_b32 s23, v247, 22
	v_mfma_f32_16x16x32_bf16 v[40:43], v[98:101], v[86:89], v[40:43]
	v_mfma_f32_16x16x32_bf16 v[56:59], v[102:105], v[86:89], v[56:59]
	v_mfma_f32_16x16x32_bf16 v[60:63], v[106:109], v[86:89], v[60:63]
	v_mfma_f32_16x16x32_bf16 v[14:17], v[110:113], v[86:89], v[16:19]
	v_mfma_f32_16x16x32_bf16 v[64:67], v[98:101], v[90:93], v[64:67]
	v_mfma_f32_16x16x32_bf16 v[68:71], v[102:105], v[90:93], v[68:71]
	v_mfma_f32_16x16x32_bf16 v[72:75], v[106:109], v[90:93], v[72:75]
	v_mfma_f32_16x16x32_bf16 v[18:21], v[110:113], v[90:93], v[20:23]
	v_mfma_f32_16x16x32_bf16 v[28:31], v[98:101], v[94:97], v[28:31]
	v_mfma_f32_16x16x32_bf16 v[32:35], v[102:105], v[94:97], v[32:35]
	v_mfma_f32_16x16x32_bf16 v[36:39], v[106:109], v[94:97], v[36:39]
	v_mfma_f32_16x16x32_bf16 v[22:25], v[110:113], v[94:97], v[24:27]
	ds_read_b128 v[82:85], v129 offset:32768
	ds_read_b128 v[86:89], v129 offset:34816
	ds_read_b128 v[90:93], v129 offset:36864
	ds_read_b128 v[94:97], v129 offset:38912
	ds_read_b128 v[98:101], v130 offset:49152
	ds_read_b128 v[102:105], v130 offset:51200
	ds_read_b128 v[106:109], v130 offset:53248
	ds_read_b128 v[110:113], v130 offset:55296
	s_waitcnt vmcnt(0)
	s_waitcnt vmcnt(0) lgkmcnt(0)
	v_mfma_f32_16x16x32_bf16 v[72:75], v[106:109], v[90:93], v[72:75]
	s_barrier
	v_mfma_f32_16x16x32_bf16 v[44:47], v[98:101], v[82:85], v[44:47]
	v_mfma_f32_16x16x32_bf16 v[48:51], v[102:105], v[82:85], v[48:51]
	v_mfma_f32_16x16x32_bf16 v[52:55], v[106:109], v[82:85], v[52:55]
	v_mfma_f32_16x16x32_bf16 v[10:13], v[110:113], v[82:85], v[10:13]
	v_mfma_f32_16x16x32_bf16 v[40:43], v[98:101], v[86:89], v[40:43]
	v_mfma_f32_16x16x32_bf16 v[56:59], v[102:105], v[86:89], v[56:59]
	v_mfma_f32_16x16x32_bf16 v[60:63], v[106:109], v[86:89], v[60:63]
	v_mfma_f32_16x16x32_bf16 v[14:17], v[110:113], v[86:89], v[14:17]
	v_mfma_f32_16x16x32_bf16 v[64:67], v[98:101], v[90:93], v[64:67]
	v_mfma_f32_16x16x32_bf16 v[68:71], v[102:105], v[90:93], v[68:71]
	v_mfma_f32_16x16x32_bf16 v[18:21], v[110:113], v[90:93], v[18:21]
	v_mfma_f32_16x16x32_bf16 v[26:29], v[98:101], v[94:97], v[28:31]
	v_mfma_f32_16x16x32_bf16 v[30:33], v[102:105], v[94:97], v[32:35]
	v_mfma_f32_16x16x32_bf16 v[34:37], v[106:109], v[94:97], v[36:39]
	v_mfma_f32_16x16x32_bf16 v[22:25], v[110:113], v[94:97], v[22:25]
	ds_read_b128 v[82:85], v130 offset:22528
	ds_read_b128 v[86:89], v130 offset:20480
	ds_read_b128 v[90:93], v130 offset:18432
	ds_read_b128 v[94:97], v130 offset:16384
	ds_read_b128 v[98:101], v129 offset:6144
	ds_read_b128 v[102:105], v129 offset:4096
	ds_read_b128 v[106:109], v129 offset:2048
	ds_read_b128 v[110:113], v129
	ds_read_b128 v[116:119], v128 offset:22528
	ds_read_b128 v[132:135], v128 offset:20480
	ds_read_b128 v[136:139], v128 offset:18432
	ds_read_b128 v[140:143], v128 offset:16384
	ds_read_b128 v[144:147], v127 offset:6144
	ds_read_b128 v[148:151], v127 offset:4096
	ds_read_b128 v[152:155], v127 offset:2048
	ds_read_b128 v[156:159], v127
	s_waitcnt vmcnt(0)
	s_waitcnt lgkmcnt(0)
	v_mfma_f32_16x16x32_bf16 v[74:77], v[132:135], v[148:151], v[72:75]
	s_barrier
; __device__ __forceinline__ float bf2f(bf16_t h) { return __uint_as_float(((unsigned)h) << 16); }
;     ...
;         for (int mi = 0; mi < 4; mi++)
; #pragma unroll
;           for (int ni = 0; ni < 4; ni++)
;             acc[mi][ni] = TR ? __builtin_amdgcn_mfma_f32_16x16x32_bf16(bfr[ni], af[mi], acc[mi][ni], 0, 0, 0)
;                              : __builtin_amdgcn_mfma_f32_16x16x32_bf16(af[mi], bfr[ni], acc[mi][ni], 0, 0, 0);
;     ...
;         const unsigned row = rb2 + mi * 16;
;         const unsigned pr = row % (unsigned)LP;
;         if constexpr (EPI == EPI_LG) {
;           const unsigned hh = (unsigned)(n0 + wn * 64) >> 6;
;           const unsigned bb = row / (unsigned)LP;
;           const bf16_t* yb = (bb < 2u) ? (e.y01 + (size_t)bb * LP * D) : (e.y23 + (size_t)(bb - 2u) * LP * D);
;           float yv[4][4], vv[4][4];
;           float s1 = 0.f;
; #pragma unroll
;           for (int ni = 0; ni < 4; ni++) {
;             const unsigned col = cb2 + ni * 16;
;             const uint2 yu = *(const uint2*)(yb + (size_t)pr * D + col);
;             const uint2 vu = *(const uint2*)(e.c0 + (row * (unsigned)RKLD + 2048 + col));
;             const float m_ = e.mu[row * 64u + hh * 4u + ni];
;             yv[ni][0] = bf2f((bf16_t)(yu.x & 0xffff)) + m_; yv[ni][1] = bf2f((bf16_t)(yu.x >> 16)) + m_;
;             yv[ni][2] = bf2f((bf16_t)(yu.y & 0xffff)) + m_; yv[ni][3] = bf2f((bf16_t)(yu.y >> 16)) + m_;
;             vv[ni][0] = bf2f((bf16_t)(vu.x & 0xffff)); vv[ni][1] = bf2f((bf16_t)(vu.x >> 16));
;             vv[ni][2] = bf2f((bf16_t)(vu.y & 0xffff)); vv[ni][3] = bf2f((bf16_t)(vu.y >> 16));
;             s1 += (yv[ni][0] + yv[ni][1]) + (yv[ni][2] + yv[ni][3]);
;           }
	v_mfma_f32_16x16x32_bf16 v[44:47], v[140:143], v[156:159], v[44:47]
	v_mfma_f32_16x16x32_bf16 v[52:55], v[132:135], v[156:159], v[52:55]
	v_mfma_f32_16x16x32_bf16 v[10:13], v[116:119], v[156:159], v[10:13]
	v_mfma_f32_16x16x32_bf16 v[166:169], v[132:135], v[152:155], v[60:63]
	v_mfma_f32_16x16x32_bf16 v[14:17], v[116:119], v[152:155], v[14:17]
	v_mfma_f32_16x16x32_bf16 v[18:21], v[116:119], v[148:151], v[18:21]
	v_mfma_f32_16x16x32_bf16 v[132:135], v[132:135], v[144:147], v[34:37]
	v_mfma_f32_16x16x32_bf16 v[116:119], v[116:119], v[144:147], v[22:25]
	v_mfma_f32_16x16x32_bf16 v[48:51], v[136:139], v[156:159], v[48:51]
	v_mfma_f32_16x16x32_bf16 v[156:159], v[136:139], v[152:155], v[56:59]
	v_mfma_f32_16x16x32_bf16 v[170:173], v[136:139], v[148:151], v[68:71]
	v_mfma_f32_16x16x32_bf16 v[136:139], v[136:139], v[144:147], v[30:33]
	v_mfma_f32_16x16x32_bf16 v[30:33], v[86:89], v[102:105], v[74:77]
	s_nop 2
	v_or_b32_e32 v74, s1, v125
	v_mul_hi_u32 v75, v8, s24
	v_readlane_b32 s0, v246, 7
	v_lshrrev_b32_e32 v76, 13, v75
	v_readlane_b32 s1, v246, 8
	v_mfma_f32_16x16x32_bf16 v[38:41], v[140:143], v[152:155], v[40:43]
	v_mfma_f32_16x16x32_bf16 v[152:155], v[140:143], v[148:151], v[64:67]
	v_mfma_f32_16x16x32_bf16 v[140:143], v[140:143], v[144:147], v[26:29]
	v_mfma_f32_16x16x32_bf16 v[70:73], v[94:97], v[110:113], v[44:47]
	v_mfma_f32_16x16x32_bf16 v[58:61], v[82:85], v[110:113], v[10:13]
	v_mfma_f32_16x16x32_bf16 v[42:45], v[82:85], v[106:109], v[14:17]
	v_mfma_f32_16x16x32_bf16 v[26:29], v[82:85], v[102:105], v[18:21]
	v_mfma_f32_16x16x32_bf16 v[14:17], v[86:89], v[98:101], v[132:135]
	v_mfma_f32_16x16x32_bf16 v[10:13], v[82:85], v[98:101], v[116:119]
	v_or_b32_e32 v84, v74, v126
	s_nop 0
	v_or_b32_e32 v135, v8, v122
	v_lshrrev_b32_e32 v133, 6, v74
	v_lshrrev_b32_e32 v134, 4, v74
	v_add_u32_e32 v8, -2, v76
	v_mov_b64_e32 v[74:75], s[0:1]
	s_mov_b32 s0, 0x1040000
	v_mad_u64_u32 v[74:75], s[0:1], v8, s0, v[74:75]
	v_readlane_b32 s0, v246, 5
	v_mul_u32_u24_e32 v8, 0x820000, v76
	v_readlane_b32 s1, v246, 6
	v_mfma_f32_16x16x32_bf16 v[18:21], v[90:93], v[98:101], v[136:139]
	v_mov_b32_e32 v85, v9
	v_lshl_add_u64 v[76:77], v[8:9], 1, s[0:1]
	v_mul_hi_u32 v8, v135, s24
	v_lshrrev_b32_e32 v8, 13, v8
	v_mul_u32_u24_e32 v8, 0x2080, v8
	v_sub_u32_e32 v138, v135, v8
	v_mfma_f32_16x16x32_bf16 v[66:69], v[90:93], v[110:113], v[48:51]
	v_lshlrev_b32_e32 v8, 11, v138
	v_or_b32_e32 v131, 32, v84
	v_or_b32_e32 v132, 48, v84
	v_mfma_f32_16x16x32_bf16 v[62:65], v[86:89], v[110:113], v[52:55]
	v_mfma_f32_16x16x32_bf16 v[46:49], v[86:89], v[106:109], v[166:169]
	v_cndmask_b32_e32 v89, v75, v77, vcc
	v_cndmask_b32_e32 v88, v74, v76, vcc
	v_lshl_add_u64 v[74:75], v[88:89], 0, v[8:9]
	v_mul_lo_u32 v8, v135, s15
	v_add_u32_e32 v114, 0x800, v8
	v_mfma_f32_16x16x32_bf16 v[50:53], v[90:93], v[106:109], v[156:159]
	v_add_u32_e32 v8, v114, v84
	v_lshlrev_b64 v[86:87], 2, v[84:85]
	v_lshl_add_u32 v76, v135, 6, v134
	v_mfma_f32_16x16x32_bf16 v[34:37], v[90:93], v[102:105], v[170:173]
	v_lshlrev_b64 v[90:91], 1, v[84:85]
	v_or_b32_e32 v85, 16, v84
	v_mov_b32_e32 v77, v9
	v_mfma_f32_16x16x32_bf16 v[54:57], v[94:97], v[106:109], v[38:41]
	v_lshl_add_u64 v[106:107], v[74:75], 0, v[90:91]
	v_lshl_add_u64 v[74:75], v[8:9], 1, s[52:53]
	global_load_dwordx2 v[92:93], v[106:107], off
	v_mfma_f32_16x16x32_bf16 v[38:41], v[94:97], v[102:105], v[152:155]
	v_add_u32_e32 v8, v114, v85
	v_lshl_add_u64 v[82:83], s[16:17], 0, v[86:87]
	v_cmp_gt_u32_e32 vcc, s14, v138
	v_mfma_f32_16x16x32_bf16 v[22:25], v[94:97], v[98:101], v[140:143]
	global_load_dwordx2 v[96:97], v[74:75], off
	v_lshl_add_u64 v[98:99], v[8:9], 1, s[52:53]
	global_load_dwordx2 v[100:101], v[98:99], off
	v_add_u32_e32 v8, v114, v131
	v_lshl_add_u64 v[74:75], v[76:77], 2, s[10:11]
	v_lshl_add_u64 v[102:103], v[8:9], 1, s[52:53]
	global_load_dwordx4 v[74:77], v[74:75], off
	v_add_u32_e32 v8, v114, v132
	global_load_dwordx2 v[108:109], v[102:103], off
	v_lshl_add_u64 v[86:87], s[18:19], 0, v[86:87]
	global_load_dwordx4 v[174:177], v[82:83], off offset:64
	global_load_dwordx4 v[178:181], v[82:83], off offset:128
	global_load_dwordx4 v[182:185], v[82:83], off offset:192
	global_load_dwordx4 v[186:189], v[86:87], off offset:64
	global_load_dwordx4 v[190:193], v[86:87], off offset:128
	global_load_dwordx4 v[194:197], v[86:87], off offset:192
	v_lshlrev_b32_e32 v154, 10, v135
	s_waitcnt vmcnt(4)
	v_lshlrev_b32_e32 v104, 16, v92
	v_and_b32_e32 v105, 0xffff0000, v92
	v_lshlrev_b32_e32 v110, 16, v93
	v_and_b32_e32 v111, 0xffff0000, v93
	s_waitcnt vmcnt(3)
	v_lshlrev_b32_e32 v94, 16, v96
	v_and_b32_e32 v95, 0xffff0000, v96
	v_lshlrev_b32_e32 v92, 16, v97
	v_and_b32_e32 v93, 0xffff0000, v97
	global_load_dwordx2 v[96:97], v[106:107], off offset:32
	s_waitcnt vmcnt(3)
	v_lshlrev_b32_e32 v98, 16, v100
	v_and_b32_e32 v99, 0xffff0000, v100
	s_waitcnt vmcnt(2)
	v_pk_add_f32 v[110:111], v[74:75], v[110:111] op_sel_hi:[0,1]
	s_waitcnt vmcnt(1)
	v_lshlrev_b32_e32 v102, 16, v108
	v_and_b32_e32 v103, 0xffff0000, v108
	v_pk_add_f32 v[104:105], v[74:75], v[104:105] op_sel_hi:[0,1]
	v_add_f32_e32 v148, v104, v105
	s_waitcnt vmcnt(0)
	v_lshlrev_b32_e32 v112, 16, v96
	v_and_b32_e32 v113, 0xffff0000, v96
	v_lshlrev_b32_e32 v116, 16, v97
	v_and_b32_e32 v117, 0xffff0000, v97
	v_lshlrev_b32_e32 v96, 16, v101
	v_and_b32_e32 v97, 0xffff0000, v101
	global_load_dwordx2 v[100:101], v[106:107], off offset:64
	v_pk_add_f32 v[116:117], v[74:75], v[116:117] op_sel:[1,0]
	global_load_dwordx2 v[106:107], v[106:107], off offset:96
	v_pk_add_f32 v[74:75], v[74:75], v[112:113] op_sel:[1,0]
	s_waitcnt vmcnt(1)
; __device__ __forceinline__ float bf2f(bf16_t h) { return __uint_as_float(((unsigned)h) << 16); }
;     ...
;           for (int ni = 0; ni < 4; ni++) {
;             const unsigned col = cb2 + ni * 16;
;             const uint2 yu = *(const uint2*)(yb + (size_t)pr * D + col);
;             const uint2 vu = *(const uint2*)(e.c0 + (row * (unsigned)RKLD + 2048 + col));
;             const float m_ = e.mu[row * 64u + hh * 4u + ni];
;             yv[ni][0] = bf2f((bf16_t)(yu.x & 0xffff)) + m_; yv[ni][1] = bf2f((bf16_t)(yu.x >> 16)) + m_;
;             yv[ni][2] = bf2f((bf16_t)(yu.y & 0xffff)) + m_; yv[ni][3] = bf2f((bf16_t)(yu.y >> 16)) + m_;
;             vv[ni][0] = bf2f((bf16_t)(vu.x & 0xffff)); vv[ni][1] = bf2f((bf16_t)(vu.x >> 16));
;             vv[ni][2] = bf2f((bf16_t)(vu.y & 0xffff)); vv[ni][3] = bf2f((bf16_t)(vu.y >> 16));
;             s1 += (yv[ni][0] + yv[ni][1]) + (yv[ni][2] + yv[ni][3]);
;           }
;           const float mean = xrow16_sum(s1) * (1.f / 64.f);
;           float s2 = 0.f;
; #pragma unroll
;           for (int ni = 0; ni < 4; ni++)
; #pragma unroll
;             for (int j = 0; j < 4; j++) { yv[ni][j] -= mean; s2 += yv[ni][j] * yv[ni][j]; }
;           const float rstd = rsqrtf(xrow16_sum(s2) * (1.f / 64.f) + 64e-5f);
;           const float sb = e.sbp[row * 16u + hh];
; #pragma unroll
;           for (int ni = 0; ni < 4; ni++) {
;             const unsigned col = cb2 + ni * 16;
;             const float4 lw = *(const float4*)(e.lnw + col), lb = *(const float4*)(e.lnb + col);
	v_lshlrev_b32_e32 v118, 16, v100
	v_and_b32_e32 v119, 0xffff0000, v100
	v_lshlrev_b32_e32 v120, 16, v101
	v_and_b32_e32 v121, 0xffff0000, v101
	v_lshlrev_b32_e32 v100, 16, v109
	v_and_b32_e32 v101, 0xffff0000, v109
	v_lshl_add_u64 v[108:109], v[8:9], 1, s[52:53]
	global_load_dwordx2 v[136:137], v[108:109], off
	v_lshl_add_u32 v8, v135, 4, v133
	s_waitcnt vmcnt(1)
	v_lshlrev_b32_e32 v144, 16, v106
	v_and_b32_e32 v145, 0xffff0000, v106
	v_lshlrev_b32_e32 v146, 16, v107
	v_and_b32_e32 v147, 0xffff0000, v107
	v_add_f32_e32 v112, v74, v75
	v_pk_add_f32 v[120:121], v[76:77], v[120:121] op_sel_hi:[0,1]
	v_pk_add_f32 v[118:119], v[76:77], v[118:119] op_sel_hi:[0,1]
	v_add_f32_e32 v76, v118, v119
	s_waitcnt vmcnt(0)
	v_lshlrev_b32_e32 v108, 16, v136
	v_and_b32_e32 v109, 0xffff0000, v136
	v_lshlrev_b32_e32 v106, 16, v137
	v_and_b32_e32 v107, 0xffff0000, v137
	v_lshl_add_u64 v[136:137], v[8:9], 2, s[12:13]
	global_load_dword v114, v[136:137], off
	s_nop 0
	global_load_dwordx4 v[136:139], v[82:83], off
	global_load_dwordx4 v[140:143], v[86:87], off
	v_add_f32_e32 v8, v110, v111
	v_add_f32_e32 v8, v148, v8
	v_add_f32_e32 v150, 0, v8
	v_add_u32_e32 v8, v154, v84
	v_lshl_add_u64 v[148:149], v[8:9], 1, s[8:9]
	v_add_f32_e32 v8, v116, v117
	v_add_f32_e32 v8, v112, v8
	v_add_f32_e32 v150, v150, v8
	v_add_u32_e32 v8, v154, v85
	v_lshl_add_u64 v[112:113], v[8:9], 1, s[8:9]
	v_add_f32_e32 v8, v120, v121
	v_add_f32_e32 v8, v76, v8
	v_add_f32_e32 v152, v150, v8
	v_add_u32_e32 v8, v154, v131
	v_lshl_add_u64 v[150:151], v[8:9], 1, s[8:9]
	v_mov_b32_e32 v8, v77
	v_pk_add_f32 v[76:77], v[8:9], v[146:147] op_sel_hi:[0,1]
	v_pk_add_f32 v[144:145], v[8:9], v[144:145] op_sel_hi:[0,1]
	v_add_f32_e32 v8, v76, v77
	v_add_f32_e32 v146, v144, v145
	v_add_f32_e32 v8, v146, v8
	v_add_f32_e32 v8, v152, v8
	v_mov_b32_e32 v146, v8
	s_nop 1
	v_permlane16_swap_b32_e32 v8, v146
	v_add_f32_e32 v8, v8, v146
	v_mov_b32_e32 v146, v8
	s_nop 1
	v_permlane32_swap_b32_e32 v8, v146
	v_add_f32_e32 v8, v8, v146
	v_mul_f32_e32 v8, 0x3c800000, v8
	v_pk_add_f32 v[104:105], v[104:105], v[8:9] op_sel_hi:[1,0] neg_lo:[0,1] neg_hi:[0,1]
	v_pk_add_f32 v[110:111], v[110:111], v[8:9] op_sel_hi:[1,0] neg_lo:[0,1] neg_hi:[0,1]
	v_mul_f32_e32 v146, v105, v105
	v_pk_fma_f32 v[146:147], v[104:105], v[104:105], v[146:147] op_sel_hi:[1,1,0]
	v_mul_f32_e32 v152, v111, v111
	v_pk_fma_f32 v[146:147], v[110:111], v[110:111], v[146:147]
	v_pk_add_f32 v[116:117], v[116:117], v[8:9] op_sel_hi:[1,0] neg_lo:[0,1] neg_hi:[0,1]
	v_pk_add_f32 v[146:147], v[152:153], v[146:147] op_sel_hi:[0,1]
	v_pk_add_f32 v[152:153], v[74:75], v[8:9] op_sel_hi:[1,0] neg_lo:[0,1] neg_hi:[0,1]
	v_pk_add_f32 v[118:119], v[118:119], v[8:9] op_sel_hi:[1,0] neg_lo:[0,1] neg_hi:[0,1]
	v_pk_fma_f32 v[74:75], v[152:153], v[152:153], v[146:147]
	v_mul_f32_e32 v146, v153, v153
	v_pk_add_f32 v[74:75], v[146:147], v[74:75] op_sel_hi:[0,1]
	v_pk_fma_f32 v[74:75], v[116:117], v[116:117], v[74:75]
	v_mul_f32_e32 v146, v117, v117
	v_pk_add_f32 v[74:75], v[146:147], v[74:75] op_sel_hi:[0,1]
	v_pk_fma_f32 v[74:75], v[118:119], v[118:119], v[74:75]
	v_mul_f32_e32 v146, v119, v119
	v_pk_add_f32 v[74:75], v[146:147], v[74:75] op_sel_hi:[0,1]
	v_pk_add_f32 v[120:121], v[120:121], v[8:9] op_sel_hi:[1,0] neg_lo:[0,1] neg_hi:[0,1]
	v_pk_add_f32 v[144:145], v[144:145], v[8:9] op_sel_hi:[1,0] neg_lo:[0,1] neg_hi:[0,1]
	v_pk_fma_f32 v[74:75], v[120:121], v[120:121], v[74:75]
	v_mul_f32_e32 v146, v121, v121
	v_pk_add_f32 v[74:75], v[146:147], v[74:75] op_sel_hi:[0,1]
	v_pk_fma_f32 v[74:75], v[144:145], v[144:145], v[74:75]
	v_mul_f32_e32 v146, v145, v145
	v_pk_add_f32 v[74:75], v[146:147], v[74:75] op_sel_hi:[0,1]
	v_pk_add_f32 v[146:147], v[76:77], v[8:9] op_sel_hi:[1,0] neg_lo:[0,1] neg_hi:[0,1]
	s_nop 0
	v_pk_fma_f32 v[74:75], v[146:147], v[146:147], v[74:75]
	v_mul_f32_e32 v8, v147, v147
	v_pk_add_f32 v[74:75], v[8:9], v[74:75] op_sel_hi:[0,1]
	v_mov_b32_e32 v8, v74
	s_nop 1
	v_permlane16_swap_b32_e32 v74, v8
	v_add_f32_e32 v8, v74, v8
	v_mov_b32_e32 v74, v8
	s_nop 1
	v_permlane32_swap_b32_e32 v8, v74
	v_add_f32_e32 v8, v8, v74
	v_fmamk_f32 v8, v8, 0x3c800000, v206
	v_cmp_gt_f32_e64 s[0:1], s5, v8
	v_mul_f32_e32 v74, 0x4b800000, v8
	s_nop 0
	v_cndmask_b32_e64 v8, v8, v74, s[0:1]
	v_rsq_f32_e32 v8, v8
	s_nop 0
	v_mul_f32_e32 v74, 0x45800000, v8
	v_cndmask_b32_e64 v8, v8, v74, s[0:1]
	v_pk_mul_f32 v[74:75], v[104:105], v[8:9] op_sel_hi:[1,0]
	s_waitcnt vmcnt(0)
; __device__ __forceinline__ float bf2f(bf16_t h) { return __uint_as_float(((unsigned)h) << 16); }
;     ...
;         const unsigned row = rb2 + mi * 16;
;         const unsigned pr = row % (unsigned)LP;
;         if constexpr (EPI == EPI_LG) {
;           const unsigned hh = (unsigned)(n0 + wn * 64) >> 6;
;           const unsigned bb = row / (unsigned)LP;
;           const bf16_t* yb = (bb < 2u) ? (e.y01 + (size_t)bb * LP * D) : (e.y23 + (size_t)(bb - 2u) * LP * D);
;           float yv[4][4], vv[4][4];
;           float s1 = 0.f;
; #pragma unroll
;           for (int ni = 0; ni < 4; ni++) {
;             const unsigned col = cb2 + ni * 16;
;             const uint2 yu = *(const uint2*)(yb + (size_t)pr * D + col);
;             const uint2 vu = *(const uint2*)(e.c0 + (row * (unsigned)RKLD + 2048 + col));
;             const float m_ = e.mu[row * 64u + hh * 4u + ni];
;             yv[ni][0] = bf2f((bf16_t)(yu.x & 0xffff)) + m_; yv[ni][1] = bf2f((bf16_t)(yu.x >> 16)) + m_;
;             yv[ni][2] = bf2f((bf16_t)(yu.y & 0xffff)) + m_; yv[ni][3] = bf2f((bf16_t)(yu.y >> 16)) + m_;
;             vv[ni][0] = bf2f((bf16_t)(vu.x & 0xffff)); vv[ni][1] = bf2f((bf16_t)(vu.x >> 16));
;             vv[ni][2] = bf2f((bf16_t)(vu.y & 0xffff)); vv[ni][3] = bf2f((bf16_t)(vu.y >> 16));
;             s1 += (yv[ni][0] + yv[ni][1]) + (yv[ni][2] + yv[ni][3]);
;           }
;     ...
;           for (int ni = 0; ni < 4; ni++) {
;             const unsigned col = cb2 + ni * 16;
;             const float4 lw = *(const float4*)(e.lnw + col), lb = *(const float4*)(e.lnb + col);
;             const f32x4 a = acc[mi][ni];
;             uint2 o;
;             o.x = pack2(a[0] * (yv[ni][0] * rstd * lw.x + lb.x + sb * vv[ni][0]), a[1] * (yv[ni][1] * rstd * lw.y + lb.y + sb * vv[ni][1]));
;             o.y = pack2(a[2] * (yv[ni][2] * rstd * lw.z + lb.z + sb * vv[ni][2]), a[3] * (yv[ni][3] * rstd * lw.w + lb.w + sb * vv[ni][3]));
;             if (pr < PADR) { o.x = 0u; o.y = 0u; }
;             *(uint2*)(e.b0 + (row * (unsigned)D + col)) = o;
	v_pk_fma_f32 v[74:75], v[136:137], v[74:75], v[140:141]
	s_nop 0
	v_pk_fma_f32 v[74:75], v[114:115], v[94:95], v[74:75] op_sel_hi:[0,1,1]
	v_pk_mul_f32 v[70:71], v[70:71], v[74:75]
	s_nop 0
	v_cvt_pk_bf16_f32 v74, v70, v71
	v_pk_mul_f32 v[70:71], v[110:111], v[8:9] op_sel_hi:[1,0]
	s_nop 0
	v_pk_fma_f32 v[70:71], v[138:139], v[70:71], v[142:143]
	s_nop 0
	v_pk_fma_f32 v[70:71], v[114:115], v[92:93], v[70:71] op_sel_hi:[0,1,1]
	v_pk_mul_f32 v[70:71], v[72:73], v[70:71]
	v_pk_mul_f32 v[92:93], v[152:153], v[8:9] op_sel_hi:[1,0]
	v_cvt_pk_bf16_f32 v70, v70, v71
	v_cndmask_b32_e64 v71, v70, 0, vcc
	v_cndmask_b32_e64 v70, v74, 0, vcc
	global_store_dwordx2 v[148:149], v[70:71], off
	s_nop 0
	s_nop 1
	v_mov_b32_e32 v70, v174
	v_mov_b32_e32 v71, v175
	v_mov_b32_e32 v72, v176
	v_mov_b32_e32 v73, v177
	v_mov_b32_e32 v74, v186
	v_mov_b32_e32 v75, v187
	v_mov_b32_e32 v76, v188
	v_mov_b32_e32 v77, v189
	v_pk_fma_f32 v[70:71], v[92:93], v[70:71], v[74:75]
	s_nop 0
	v_pk_fma_f32 v[70:71], v[114:115], v[98:99], v[70:71] op_sel_hi:[0,1,1]
	v_pk_mul_f32 v[66:67], v[66:67], v[70:71]
	v_pk_mul_f32 v[74:75], v[118:119], v[8:9] op_sel_hi:[1,0]
	v_cvt_pk_bf16_f32 v70, v66, v67
	v_pk_mul_f32 v[66:67], v[116:117], v[8:9] op_sel_hi:[1,0]
	s_nop 0
	v_pk_fma_f32 v[66:67], v[66:67], v[72:73], v[76:77]
	s_nop 0
	v_pk_fma_f32 v[66:67], v[114:115], v[96:97], v[66:67] op_sel_hi:[0,1,1]
	v_pk_mul_f32 v[66:67], v[68:69], v[66:67]
	s_nop 0
	v_cvt_pk_bf16_f32 v66, v66, v67
	v_cndmask_b32_e64 v67, v66, 0, vcc
	v_cndmask_b32_e64 v66, v70, 0, vcc
	global_store_dwordx2 v[112:113], v[66:67], off
	s_nop 0
	s_nop 1
	v_mov_b32_e32 v66, v178
	v_mov_b32_e32 v67, v179
	v_mov_b32_e32 v68, v180
	v_mov_b32_e32 v69, v181
	v_mov_b32_e32 v70, v190
	v_mov_b32_e32 v71, v191
	v_mov_b32_e32 v72, v192
	v_mov_b32_e32 v73, v193
	v_pk_fma_f32 v[66:67], v[74:75], v[66:67], v[70:71]
	s_nop 0
	v_pk_fma_f32 v[66:67], v[114:115], v[102:103], v[66:67] op_sel_hi:[0,1,1]
	v_pk_mul_f32 v[62:63], v[62:63], v[66:67]
	v_pk_mul_f32 v[70:71], v[144:145], v[8:9] op_sel_hi:[1,0]
	v_cvt_pk_bf16_f32 v66, v62, v63
	v_pk_mul_f32 v[62:63], v[120:121], v[8:9] op_sel_hi:[1,0]
	s_nop 0
	v_pk_fma_f32 v[62:63], v[62:63], v[68:69], v[72:73]
	s_nop 0
	v_pk_fma_f32 v[62:63], v[114:115], v[100:101], v[62:63] op_sel_hi:[0,1,1]
	v_pk_mul_f32 v[62:63], v[64:65], v[62:63]
	s_nop 0
	v_cvt_pk_bf16_f32 v62, v62, v63
	v_cndmask_b32_e64 v63, v62, 0, vcc
	v_cndmask_b32_e64 v62, v66, 0, vcc
	global_store_dwordx2 v[150:151], v[62:63], off
	s_nop 0
	s_nop 1
	v_mov_b32_e32 v62, v182
	v_mov_b32_e32 v63, v183
	v_mov_b32_e32 v64, v184
	v_mov_b32_e32 v65, v185
	v_mov_b32_e32 v66, v194
	v_mov_b32_e32 v67, v195
	v_mov_b32_e32 v68, v196
	v_mov_b32_e32 v69, v197
	v_pk_fma_f32 v[62:63], v[70:71], v[62:63], v[66:67]
	s_nop 0
	v_pk_fma_f32 v[62:63], v[114:115], v[108:109], v[62:63] op_sel_hi:[0,1,1]
	v_pk_mul_f32 v[58:59], v[58:59], v[62:63]
	s_nop 0
	v_cvt_pk_bf16_f32 v62, v58, v59
	v_pk_mul_f32 v[58:59], v[146:147], v[8:9] op_sel_hi:[1,0]
	s_nop 0
	v_pk_fma_f32 v[58:59], v[58:59], v[64:65], v[68:69]
	s_nop 0
	v_pk_fma_f32 v[58:59], v[114:115], v[106:107], v[58:59] op_sel_hi:[0,1,1]
	v_pk_mul_f32 v[58:59], v[60:61], v[58:59]
	s_nop 0
	v_cvt_pk_bf16_f32 v8, v58, v59
	v_cndmask_b32_e64 v59, v8, 0, vcc
	v_add_u32_e32 v8, v154, v132
	v_cndmask_b32_e64 v58, v62, 0, vcc
	v_lshl_add_u64 v[60:61], v[8:9], 1, s[8:9]
	global_store_dwordx2 v[60:61], v[58:59], off
	v_or_b32_e32 v113, 16, v135
	v_mul_hi_u32 v8, v113, s24
	v_lshrrev_b32_e32 v8, 13, v8
	v_mul_u32_u24_e32 v8, 0x2080, v8
	v_sub_u32_e32 v117, v113, v8
	v_lshlrev_b32_e32 v8, 11, v117
	v_lshl_add_u64 v[58:59], v[88:89], 0, v[8:9]
	v_mul_lo_u32 v8, v113, s15
	v_add_u32_e32 v70, 0x800, v8
	v_lshl_add_u64 v[58:59], v[58:59], 0, v[90:91]
	v_add_u32_e32 v8, v70, v84
	global_load_dwordx2 v[92:93], v[58:59], off
	v_lshl_add_u64 v[60:61], v[8:9], 1, s[52:53]
	global_load_dwordx2 v[94:95], v[60:61], off
	global_load_dwordx2 v[96:97], v[58:59], off offset:32
	global_load_dwordx2 v[98:99], v[58:59], off offset:64
	global_load_dwordx2 v[100:101], v[58:59], off offset:96
	v_mov_b32_e32 v59, v9
	v_lshl_add_u32 v58, v113, 6, v134
	v_lshl_add_u64 v[58:59], v[58:59], 2, s[10:11]
	global_load_dwordx4 v[74:77], v[58:59], off
	s_nop 0
	global_load_dwordx4 v[58:61], v[82:83], off
	global_load_dwordx4 v[62:65], v[86:87], off
	v_add_u32_e32 v8, v70, v85
	v_lshl_add_u64 v[66:67], v[8:9], 1, s[52:53]
	v_add_u32_e32 v8, v70, v131
	v_lshl_add_u64 v[68:69], v[8:9], 1, s[52:53]
	v_add_u32_e32 v8, v70, v132
	v_lshl_add_u64 v[102:103], v[8:9], 1, s[52:53]
	v_lshl_add_u32 v8, v113, 4, v133
	v_lshl_add_u64 v[104:105], v[8:9], 2, s[12:13]
	global_load_dwordx2 v[72:73], v[66:67], off
	global_load_dwordx2 v[70:71], v[68:69], off
	s_nop 0
	global_load_dwordx2 v[68:69], v[102:103], off
	global_load_dword v66, v[104:105], off
	s_waitcnt vmcnt(10)
	v_lshlrev_b32_e32 v104, 16, v94
	v_lshlrev_b32_e32 v102, 16, v92
	v_and_b32_e32 v103, 0xffff0000, v92
	v_lshlrev_b32_e32 v92, 16, v93
	v_and_b32_e32 v93, 0xffff0000, v93
	s_waitcnt vmcnt(9)
	v_lshlrev_b32_e32 v106, 16, v96
	v_and_b32_e32 v107, 0xffff0000, v96
	v_lshlrev_b32_e32 v96, 16, v97
	v_and_b32_e32 v97, 0xffff0000, v97
	s_waitcnt vmcnt(7)
	v_lshlrev_b32_e32 v110, 16, v100
	v_and_b32_e32 v111, 0xffff0000, v100
	v_lshlrev_b32_e32 v100, 16, v101
	v_and_b32_e32 v101, 0xffff0000, v101
	s_waitcnt vmcnt(6)
;     ...
;           const float mean = xrow16_sum(s1) * (1.f / 64.f);
;           float s2 = 0.f;
; #pragma unroll
;           for (int ni = 0; ni < 4; ni++)
; #pragma unroll
;             for (int j = 0; j < 4; j++) { yv[ni][j] -= mean; s2 += yv[ni][j] * yv[ni][j]; }
;           const float rstd = rsqrtf(xrow16_sum(s2) * (1.f / 64.f) + 64e-5f);
;           const float sb = e.sbp[row * 16u + hh];
; #pragma unroll
;           for (int ni = 0; ni < 4; ni++) {
;             const unsigned col = cb2 + ni * 16;
;             const float4 lw = *(const float4*)(e.lnw + col), lb = *(const float4*)(e.lnb + col);
;             const f32x4 a = acc[mi][ni];
;             uint2 o;
;             o.x = pack2(a[0] * (yv[ni][0] * rstd * lw.x + lb.x + sb * vv[ni][0]), a[1] * (yv[ni][1] * rstd * lw.y + lb.y + sb * vv[ni][1]));
;             o.y = pack2(a[2] * (yv[ni][2] * rstd * lw.z + lb.z + sb * vv[ni][2]), a[3] * (yv[ni][3] * rstd * lw.w + lb.w + sb * vv[ni][3]));
;             if (pr < PADR) { o.x = 0u; o.y = 0u; }
;             *(uint2*)(e.b0 + (row * (unsigned)D + col)) = o;
	v_mov_b32_e32 v8, v77
	v_pk_add_f32 v[92:93], v[74:75], v[92:93] op_sel_hi:[0,1]
	v_pk_add_f32 v[102:103], v[74:75], v[102:103] op_sel_hi:[0,1]
	v_lshlrev_b32_e32 v108, 16, v98
	v_and_b32_e32 v109, 0xffff0000, v98
	v_lshlrev_b32_e32 v98, 16, v99
	v_and_b32_e32 v99, 0xffff0000, v99
	v_pk_add_f32 v[96:97], v[74:75], v[96:97] op_sel:[1,0]
	v_pk_add_f32 v[74:75], v[74:75], v[106:107] op_sel:[1,0]
	v_pk_add_f32 v[100:101], v[8:9], v[100:101] op_sel_hi:[0,1]
	v_pk_add_f32 v[106:107], v[8:9], v[110:111] op_sel_hi:[0,1]
	v_add_f32_e32 v8, v92, v93
	v_add_f32_e32 v67, v102, v103
	v_pk_add_f32 v[98:99], v[76:77], v[98:99] op_sel_hi:[0,1]
	v_pk_add_f32 v[76:77], v[76:77], v[108:109] op_sel_hi:[0,1]
	v_add_f32_e32 v108, v96, v97
	v_add_f32_e32 v109, v74, v75
	v_add_f32_e32 v8, v67, v8
	v_add_f32_e32 v110, v98, v99
	v_add_f32_e32 v111, v76, v77
	v_add_f32_e32 v67, v109, v108
	v_add_f32_e32 v8, 0, v8
	v_add_f32_e32 v112, v100, v101
	v_add_f32_e32 v114, v106, v107
	v_add_f32_e32 v108, v111, v110
	v_add_f32_e32 v8, v8, v67
	v_add_f32_e32 v109, v114, v112
	v_add_f32_e32 v8, v8, v108
	v_add_f32_e32 v8, v8, v109
	v_mov_b32_e32 v67, v8
	s_nop 1
	v_permlane16_swap_b32_e32 v8, v67
	v_add_f32_e32 v8, v8, v67
	v_mov_b32_e32 v67, v8
	s_nop 1
	v_permlane32_swap_b32_e32 v8, v67
	v_add_f32_e32 v8, v8, v67
	v_mul_f32_e32 v8, 0x3c800000, v8
	v_pk_add_f32 v[102:103], v[102:103], v[8:9] op_sel_hi:[1,0] neg_lo:[0,1] neg_hi:[0,1]
	v_pk_add_f32 v[92:93], v[92:93], v[8:9] op_sel_hi:[1,0] neg_lo:[0,1] neg_hi:[0,1]
	v_pk_add_f32 v[74:75], v[74:75], v[8:9] op_sel_hi:[1,0] neg_lo:[0,1] neg_hi:[0,1]
	v_pk_add_f32 v[96:97], v[96:97], v[8:9] op_sel_hi:[1,0] neg_lo:[0,1] neg_hi:[0,1]
	v_pk_add_f32 v[76:77], v[76:77], v[8:9] op_sel_hi:[1,0] neg_lo:[0,1] neg_hi:[0,1]
	v_pk_add_f32 v[98:99], v[98:99], v[8:9] op_sel_hi:[1,0] neg_lo:[0,1] neg_hi:[0,1]
	v_pk_add_f32 v[106:107], v[106:107], v[8:9] op_sel_hi:[1,0] neg_lo:[0,1] neg_hi:[0,1]
	v_pk_add_f32 v[100:101], v[100:101], v[8:9] op_sel_hi:[1,0] neg_lo:[0,1] neg_hi:[0,1]
	v_mul_f32_e32 v8, v103, v103
	v_pk_fma_f32 v[136:137], v[102:103], v[102:103], v[8:9] op_sel_hi:[1,1,0]
	v_mul_f32_e32 v108, v93, v93
	v_pk_fma_f32 v[136:137], v[92:93], v[92:93], v[136:137]
	v_mul_f32_e32 v110, v75, v75
	v_pk_add_f32 v[108:109], v[108:109], v[136:137] op_sel_hi:[0,1]
	v_pk_fma_f32 v[108:109], v[74:75], v[74:75], v[108:109]
	v_mul_f32_e32 v112, v97, v97
	v_pk_add_f32 v[108:109], v[110:111], v[108:109] op_sel_hi:[0,1]
	v_pk_fma_f32 v[108:109], v[96:97], v[96:97], v[108:109]
	v_mul_f32_e32 v114, v77, v77
	v_pk_add_f32 v[108:109], v[112:113], v[108:109] op_sel_hi:[0,1]
	v_pk_fma_f32 v[108:109], v[76:77], v[76:77], v[108:109]
	v_mul_f32_e32 v116, v99, v99
	v_pk_add_f32 v[108:109], v[114:115], v[108:109] op_sel_hi:[0,1]
	v_pk_fma_f32 v[108:109], v[98:99], v[98:99], v[108:109]
	v_mul_f32_e32 v118, v107, v107
	v_pk_add_f32 v[108:109], v[116:117], v[108:109] op_sel_hi:[0,1]
	v_pk_fma_f32 v[108:109], v[106:107], v[106:107], v[108:109]
	v_mul_f32_e32 v120, v101, v101
	v_pk_add_f32 v[108:109], v[118:119], v[108:109] op_sel_hi:[0,1]
	v_pk_fma_f32 v[108:109], v[100:101], v[100:101], v[108:109]
	v_lshlrev_b32_e32 v111, 10, v113
	v_pk_add_f32 v[108:109], v[120:121], v[108:109] op_sel_hi:[0,1]
	v_mov_b32_e32 v8, v108
	s_nop 1
	v_permlane16_swap_b32_e32 v108, v8
	v_add_f32_e32 v8, v108, v8
	v_mov_b32_e32 v67, v8
	s_nop 1
	v_permlane32_swap_b32_e32 v8, v67
	v_add_f32_e32 v8, v8, v67
	v_fmamk_f32 v8, v8, 0x3c800000, v206
	v_mul_f32_e32 v67, 0x4b800000, v8
	v_cmp_gt_f32_e32 vcc, s5, v8
	v_and_b32_e32 v105, 0xffff0000, v94
	v_lshlrev_b32_e32 v94, 16, v95
	v_cndmask_b32_e32 v8, v8, v67, vcc
	v_rsq_f32_e32 v67, v8
	v_add_u32_e32 v8, v111, v84
	v_lshl_add_u64 v[108:109], v[8:9], 1, s[8:9]
	v_and_b32_e32 v95, 0xffff0000, v95
	v_mul_f32_e32 v8, 0x45800000, v67
	v_cndmask_b32_e32 v110, v67, v8, vcc
	v_pk_mul_f32 v[102:103], v[102:103], v[110:111] op_sel_hi:[1,0]
	v_cmp_gt_u32_e32 vcc, s14, v117
	s_waitcnt vmcnt(4)
	v_pk_fma_f32 v[58:59], v[58:59], v[102:103], v[62:63]
	v_pk_mul_f32 v[74:75], v[74:75], v[110:111] op_sel_hi:[1,0]
	s_waitcnt vmcnt(0)
	v_pk_fma_f32 v[58:59], v[66:67], v[104:105], v[58:59] op_sel_hi:[0,1,1]
	v_pk_mul_f32 v[54:55], v[54:55], v[58:59]
	s_nop 0
	v_cvt_pk_bf16_f32 v8, v54, v55
	v_pk_mul_f32 v[54:55], v[92:93], v[110:111] op_sel_hi:[1,0]
	v_pk_mul_f32 v[92:93], v[96:97], v[110:111] op_sel_hi:[1,0]
	v_pk_fma_f32 v[54:55], v[60:61], v[54:55], v[64:65]
	v_lshlrev_b32_e32 v64, 16, v72
	v_pk_fma_f32 v[54:55], v[66:67], v[94:95], v[54:55] op_sel_hi:[0,1,1]
	v_pk_mul_f32 v[54:55], v[56:57], v[54:55]
	v_and_b32_e32 v65, 0xffff0000, v72
	v_cvt_pk_bf16_f32 v54, v54, v55
	v_cndmask_b32_e64 v55, v54, 0, vcc
	v_cndmask_b32_e64 v54, v8, 0, vcc
	global_store_dwordx2 v[108:109], v[54:55], off
	s_nop 0
	v_lshlrev_b32_e32 v72, 16, v73
	v_and_b32_e32 v73, 0xffff0000, v73
	v_add_u32_e32 v8, v111, v85
	v_lshl_add_u64 v[62:63], v[8:9], 1, s[8:9]
	s_nop 1
	v_mov_b32_e32 v54, v174
	v_mov_b32_e32 v55, v175
	v_mov_b32_e32 v56, v176
	v_mov_b32_e32 v57, v177
	v_mov_b32_e32 v58, v186
	v_mov_b32_e32 v59, v187
	v_mov_b32_e32 v60, v188
	v_mov_b32_e32 v61, v189
	v_pk_fma_f32 v[54:55], v[74:75], v[54:55], v[58:59]
	v_pk_fma_f32 v[56:57], v[92:93], v[56:57], v[60:61]
	v_pk_fma_f32 v[54:55], v[66:67], v[64:65], v[54:55] op_sel_hi:[0,1,1]
	v_pk_fma_f32 v[56:57], v[66:67], v[72:73], v[56:57] op_sel_hi:[0,1,1]
	v_pk_mul_f32 v[50:51], v[50:51], v[54:55]
	v_pk_mul_f32 v[52:53], v[52:53], v[56:57]
	v_cvt_pk_bf16_f32 v8, v50, v51
	v_cvt_pk_bf16_f32 v50, v52, v53
	v_cndmask_b32_e64 v51, v50, 0, vcc
	v_cndmask_b32_e64 v50, v8, 0, vcc
	global_store_dwordx2 v[62:63], v[50:51], off
	s_nop 0
; __device__ __forceinline__ float bf2f(bf16_t h) { return __uint_as_float(((unsigned)h) << 16); }
;     ...
;         const unsigned row = rb2 + mi * 16;
;         const unsigned pr = row % (unsigned)LP;
;         if constexpr (EPI == EPI_LG) {
;           const unsigned hh = (unsigned)(n0 + wn * 64) >> 6;
;           const unsigned bb = row / (unsigned)LP;
;           const bf16_t* yb = (bb < 2u) ? (e.y01 + (size_t)bb * LP * D) : (e.y23 + (size_t)(bb - 2u) * LP * D);
;           float yv[4][4], vv[4][4];
;           float s1 = 0.f;
; #pragma unroll
;           for (int ni = 0; ni < 4; ni++) {
;             const unsigned col = cb2 + ni * 16;
;             const uint2 yu = *(const uint2*)(yb + (size_t)pr * D + col);
;             const uint2 vu = *(const uint2*)(e.c0 + (row * (unsigned)RKLD + 2048 + col));
;             const float m_ = e.mu[row * 64u + hh * 4u + ni];
;             yv[ni][0] = bf2f((bf16_t)(yu.x & 0xffff)) + m_; yv[ni][1] = bf2f((bf16_t)(yu.x >> 16)) + m_;
;             yv[ni][2] = bf2f((bf16_t)(yu.y & 0xffff)) + m_; yv[ni][3] = bf2f((bf16_t)(yu.y >> 16)) + m_;
;             vv[ni][0] = bf2f((bf16_t)(vu.x & 0xffff)); vv[ni][1] = bf2f((bf16_t)(vu.x >> 16));
;             vv[ni][2] = bf2f((bf16_t)(vu.y & 0xffff)); vv[ni][3] = bf2f((bf16_t)(vu.y >> 16));
;             s1 += (yv[ni][0] + yv[ni][1]) + (yv[ni][2] + yv[ni][3]);
;           }
;           const float mean = xrow16_sum(s1) * (1.f / 64.f);
;     ...
;           for (int ni = 0; ni < 4; ni++) {
;             const unsigned col = cb2 + ni * 16;
;             const float4 lw = *(const float4*)(e.lnw + col), lb = *(const float4*)(e.lnb + col);
;             const f32x4 a = acc[mi][ni];
;             uint2 o;
;             o.x = pack2(a[0] * (yv[ni][0] * rstd * lw.x + lb.x + sb * vv[ni][0]), a[1] * (yv[ni][1] * rstd * lw.y + lb.y + sb * vv[ni][1]));
;             o.y = pack2(a[2] * (yv[ni][2] * rstd * lw.z + lb.z + sb * vv[ni][2]), a[3] * (yv[ni][3] * rstd * lw.w + lb.w + sb * vv[ni][3]));
;             if (pr < PADR) { o.x = 0u; o.y = 0u; }
;             *(uint2*)(e.b0 + (row * (unsigned)D + col)) = o;
	v_lshlrev_b32_e32 v60, 16, v70
	v_and_b32_e32 v61, 0xffff0000, v70
	v_lshlrev_b32_e32 v62, 16, v71
	v_and_b32_e32 v63, 0xffff0000, v71
	v_pk_mul_f32 v[64:65], v[76:77], v[110:111] op_sel_hi:[1,0]
	v_pk_mul_f32 v[70:71], v[98:99], v[110:111] op_sel_hi:[1,0]
	v_add_u32_e32 v8, v111, v131
	v_lshl_add_u64 v[58:59], v[8:9], 1, s[8:9]
	s_nop 1
	v_mov_b32_e32 v50, v178
	v_mov_b32_e32 v51, v179
	v_mov_b32_e32 v52, v180
	v_mov_b32_e32 v53, v181
	v_mov_b32_e32 v54, v190
	v_mov_b32_e32 v55, v191
	v_mov_b32_e32 v56, v192
	v_mov_b32_e32 v57, v193
	v_pk_fma_f32 v[50:51], v[64:65], v[50:51], v[54:55]
	v_pk_fma_f32 v[52:53], v[70:71], v[52:53], v[56:57]
	v_pk_fma_f32 v[50:51], v[66:67], v[60:61], v[50:51] op_sel_hi:[0,1,1]
	v_pk_fma_f32 v[52:53], v[66:67], v[62:63], v[52:53] op_sel_hi:[0,1,1]
	v_pk_mul_f32 v[46:47], v[46:47], v[50:51]
	v_pk_mul_f32 v[48:49], v[48:49], v[52:53]
	v_cvt_pk_bf16_f32 v8, v46, v47
	v_cvt_pk_bf16_f32 v46, v48, v49
	v_cndmask_b32_e64 v47, v46, 0, vcc
	v_cndmask_b32_e64 v46, v8, 0, vcc
	global_store_dwordx2 v[58:59], v[46:47], off
	s_nop 0
	v_pk_mul_f32 v[58:59], v[106:107], v[110:111] op_sel_hi:[1,0]
	v_pk_mul_f32 v[60:61], v[100:101], v[110:111] op_sel_hi:[1,0]
	v_lshlrev_b32_e32 v54, 16, v68
	v_and_b32_e32 v55, 0xffff0000, v68
	v_lshlrev_b32_e32 v56, 16, v69
	v_and_b32_e32 v57, 0xffff0000, v69
	v_add_u32_e32 v8, v111, v132
	s_nop 1
	v_mov_b32_e32 v46, v182
	v_mov_b32_e32 v47, v183
	v_mov_b32_e32 v48, v184
	v_mov_b32_e32 v49, v185
	v_mov_b32_e32 v50, v194
	v_mov_b32_e32 v51, v195
	v_mov_b32_e32 v52, v196
	v_mov_b32_e32 v53, v197
	v_pk_fma_f32 v[46:47], v[58:59], v[46:47], v[50:51]
	v_pk_fma_f32 v[48:49], v[60:61], v[48:49], v[52:53]
	v_pk_fma_f32 v[46:47], v[66:67], v[54:55], v[46:47] op_sel_hi:[0,1,1]
	v_pk_fma_f32 v[48:49], v[66:67], v[56:57], v[48:49] op_sel_hi:[0,1,1]
	v_pk_mul_f32 v[42:43], v[42:43], v[46:47]
	v_pk_mul_f32 v[44:45], v[44:45], v[48:49]
	v_cvt_pk_bf16_f32 v42, v42, v43
	v_cvt_pk_bf16_f32 v43, v44, v45
	v_cndmask_b32_e64 v43, v43, 0, vcc
	v_cndmask_b32_e64 v42, v42, 0, vcc
	v_lshl_add_u64 v[44:45], v[8:9], 1, s[8:9]
	global_store_dwordx2 v[44:45], v[42:43], off
	v_or_b32_e32 v97, 32, v135
	v_mul_hi_u32 v8, v97, s24
	v_lshrrev_b32_e32 v8, 13, v8
	v_mul_u32_u24_e32 v8, 0x2080, v8
	v_sub_u32_e32 v99, v97, v8
	v_lshlrev_b32_e32 v8, 11, v99
	v_lshl_add_u64 v[42:43], v[88:89], 0, v[8:9]
	v_mul_lo_u32 v8, v97, s15
	v_add_u32_e32 v54, 0x800, v8
	v_lshl_add_u64 v[42:43], v[42:43], 0, v[90:91]
	v_add_u32_e32 v8, v54, v84
	global_load_dwordx2 v[62:63], v[42:43], off
	v_lshl_add_u64 v[44:45], v[8:9], 1, s[52:53]
	global_load_dwordx2 v[64:65], v[44:45], off
	global_load_dwordx2 v[66:67], v[42:43], off offset:32
	global_load_dwordx2 v[68:69], v[42:43], off offset:64
	global_load_dwordx2 v[70:71], v[42:43], off offset:96
	v_mov_b32_e32 v43, v9
	v_lshl_add_u32 v42, v97, 6, v134
	v_lshl_add_u64 v[42:43], v[42:43], 2, s[10:11]
	global_load_dwordx4 v[58:61], v[42:43], off
	s_nop 0
	global_load_dwordx4 v[42:45], v[82:83], off
	global_load_dwordx4 v[46:49], v[86:87], off
	v_add_u32_e32 v8, v54, v85
	v_lshl_add_u64 v[50:51], v[8:9], 1, s[52:53]
	v_add_u32_e32 v8, v54, v131
	v_lshl_add_u64 v[52:53], v[8:9], 1, s[52:53]
	v_add_u32_e32 v8, v54, v132
	v_lshl_add_u64 v[72:73], v[8:9], 1, s[52:53]
	v_lshl_add_u32 v8, v97, 4, v133
	v_lshl_add_u64 v[74:75], v[8:9], 2, s[12:13]
	global_load_dwordx2 v[56:57], v[50:51], off
	global_load_dwordx2 v[54:55], v[52:53], off
	s_nop 0
	global_load_dwordx2 v[52:53], v[72:73], off
	global_load_dword v50, v[74:75], off
	s_waitcnt vmcnt(10)
	v_lshlrev_b32_e32 v74, 16, v64
	v_lshlrev_b32_e32 v72, 16, v62
	v_and_b32_e32 v73, 0xffff0000, v62
	v_lshlrev_b32_e32 v62, 16, v63
	v_and_b32_e32 v63, 0xffff0000, v63
	s_waitcnt vmcnt(9)
	v_lshlrev_b32_e32 v76, 16, v66
	v_and_b32_e32 v77, 0xffff0000, v66
	v_lshlrev_b32_e32 v66, 16, v67
	v_and_b32_e32 v67, 0xffff0000, v67
	s_waitcnt vmcnt(7)
	v_lshlrev_b32_e32 v94, 16, v70
	v_and_b32_e32 v95, 0xffff0000, v70
	v_lshlrev_b32_e32 v70, 16, v71
	v_and_b32_e32 v71, 0xffff0000, v71
	s_waitcnt vmcnt(6)
	v_mov_b32_e32 v8, v61
	v_pk_add_f32 v[62:63], v[58:59], v[62:63] op_sel_hi:[0,1]
	v_pk_add_f32 v[72:73], v[58:59], v[72:73] op_sel_hi:[0,1]
	v_lshlrev_b32_e32 v92, 16, v68
	v_and_b32_e32 v93, 0xffff0000, v68
	v_lshlrev_b32_e32 v68, 16, v69
	v_and_b32_e32 v69, 0xffff0000, v69
	v_pk_add_f32 v[66:67], v[58:59], v[66:67] op_sel:[1,0]
	v_pk_add_f32 v[58:59], v[58:59], v[76:77] op_sel:[1,0]
	v_pk_add_f32 v[70:71], v[8:9], v[70:71] op_sel_hi:[0,1]
	v_pk_add_f32 v[76:77], v[8:9], v[94:95] op_sel_hi:[0,1]
	v_add_f32_e32 v8, v62, v63
	v_add_f32_e32 v51, v72, v73
	v_pk_add_f32 v[68:69], v[60:61], v[68:69] op_sel_hi:[0,1]
	v_pk_add_f32 v[60:61], v[60:61], v[92:93] op_sel_hi:[0,1]
	v_add_f32_e32 v92, v66, v67
	v_add_f32_e32 v93, v58, v59
	v_add_f32_e32 v8, v51, v8
	v_add_f32_e32 v94, v68, v69
	v_add_f32_e32 v95, v60, v61
	v_add_f32_e32 v51, v93, v92
	v_add_f32_e32 v8, 0, v8
	v_add_f32_e32 v96, v70, v71
	v_add_f32_e32 v98, v76, v77
	v_add_f32_e32 v92, v95, v94
	v_add_f32_e32 v8, v8, v51
	v_add_f32_e32 v93, v98, v96
	v_add_f32_e32 v8, v8, v92
	v_add_f32_e32 v8, v8, v93
	v_mov_b32_e32 v51, v8
	s_nop 1
	v_permlane16_swap_b32_e32 v8, v51
	v_add_f32_e32 v8, v8, v51
	v_mov_b32_e32 v51, v8
	s_nop 1
	v_permlane32_swap_b32_e32 v8, v51
	v_add_f32_e32 v8, v8, v51
	v_mul_f32_e32 v8, 0x3c800000, v8
	v_pk_add_f32 v[72:73], v[72:73], v[8:9] op_sel_hi:[1,0] neg_lo:[0,1] neg_hi:[0,1]
	v_pk_add_f32 v[62:63], v[62:63], v[8:9] op_sel_hi:[1,0] neg_lo:[0,1] neg_hi:[0,1]
	v_pk_add_f32 v[58:59], v[58:59], v[8:9] op_sel_hi:[1,0] neg_lo:[0,1] neg_hi:[0,1]
	v_pk_add_f32 v[66:67], v[66:67], v[8:9] op_sel_hi:[1,0] neg_lo:[0,1] neg_hi:[0,1]
;     ...
;           const float mean = xrow16_sum(s1) * (1.f / 64.f);
;           float s2 = 0.f;
; #pragma unroll
;           for (int ni = 0; ni < 4; ni++)
; #pragma unroll
;             for (int j = 0; j < 4; j++) { yv[ni][j] -= mean; s2 += yv[ni][j] * yv[ni][j]; }
;           const float rstd = rsqrtf(xrow16_sum(s2) * (1.f / 64.f) + 64e-5f);
;           const float sb = e.sbp[row * 16u + hh];
; #pragma unroll
;           for (int ni = 0; ni < 4; ni++) {
;             const unsigned col = cb2 + ni * 16;
;             const float4 lw = *(const float4*)(e.lnw + col), lb = *(const float4*)(e.lnb + col);
;             const f32x4 a = acc[mi][ni];
;             uint2 o;
;             o.x = pack2(a[0] * (yv[ni][0] * rstd * lw.x + lb.x + sb * vv[ni][0]), a[1] * (yv[ni][1] * rstd * lw.y + lb.y + sb * vv[ni][1]));
;             o.y = pack2(a[2] * (yv[ni][2] * rstd * lw.z + lb.z + sb * vv[ni][2]), a[3] * (yv[ni][3] * rstd * lw.w + lb.w + sb * vv[ni][3]));
;             if (pr < PADR) { o.x = 0u; o.y = 0u; }
;             *(uint2*)(e.b0 + (row * (unsigned)D + col)) = o;
	v_pk_add_f32 v[60:61], v[60:61], v[8:9] op_sel_hi:[1,0] neg_lo:[0,1] neg_hi:[0,1]
	v_pk_add_f32 v[68:69], v[68:69], v[8:9] op_sel_hi:[1,0] neg_lo:[0,1] neg_hi:[0,1]
	v_pk_add_f32 v[76:77], v[76:77], v[8:9] op_sel_hi:[1,0] neg_lo:[0,1] neg_hi:[0,1]
	v_pk_add_f32 v[70:71], v[70:71], v[8:9] op_sel_hi:[1,0] neg_lo:[0,1] neg_hi:[0,1]
	v_mul_f32_e32 v8, v73, v73
	v_pk_fma_f32 v[106:107], v[72:73], v[72:73], v[8:9] op_sel_hi:[1,1,0]
	v_mul_f32_e32 v92, v63, v63
	v_pk_fma_f32 v[106:107], v[62:63], v[62:63], v[106:107]
	v_mul_f32_e32 v94, v59, v59
	v_pk_add_f32 v[92:93], v[92:93], v[106:107] op_sel_hi:[0,1]
	v_pk_fma_f32 v[92:93], v[58:59], v[58:59], v[92:93]
	v_mul_f32_e32 v96, v67, v67
	v_pk_add_f32 v[92:93], v[94:95], v[92:93] op_sel_hi:[0,1]
	v_pk_fma_f32 v[92:93], v[66:67], v[66:67], v[92:93]
	v_mul_f32_e32 v98, v61, v61
	v_pk_add_f32 v[92:93], v[96:97], v[92:93] op_sel_hi:[0,1]
	v_pk_fma_f32 v[92:93], v[60:61], v[60:61], v[92:93]
	v_mul_f32_e32 v100, v69, v69
	v_pk_add_f32 v[92:93], v[98:99], v[92:93] op_sel_hi:[0,1]
	v_pk_fma_f32 v[92:93], v[68:69], v[68:69], v[92:93]
	v_mul_f32_e32 v102, v77, v77
	v_pk_add_f32 v[92:93], v[100:101], v[92:93] op_sel_hi:[0,1]
	v_pk_fma_f32 v[92:93], v[76:77], v[76:77], v[92:93]
	v_mul_f32_e32 v104, v71, v71
	v_pk_add_f32 v[92:93], v[102:103], v[92:93] op_sel_hi:[0,1]
	v_pk_fma_f32 v[92:93], v[70:71], v[70:71], v[92:93]
	v_lshlrev_b32_e32 v95, 10, v97
	v_pk_add_f32 v[92:93], v[104:105], v[92:93] op_sel_hi:[0,1]
	v_mov_b32_e32 v8, v92
	s_nop 1
	v_permlane16_swap_b32_e32 v92, v8
	v_add_f32_e32 v8, v92, v8
	v_mov_b32_e32 v51, v8
	s_nop 1
	v_permlane32_swap_b32_e32 v8, v51
	v_add_f32_e32 v8, v8, v51
	v_fmamk_f32 v8, v8, 0x3c800000, v206
	v_mul_f32_e32 v51, 0x4b800000, v8
	v_cmp_gt_f32_e32 vcc, s5, v8
	v_and_b32_e32 v75, 0xffff0000, v64
	v_lshlrev_b32_e32 v64, 16, v65
	v_cndmask_b32_e32 v8, v8, v51, vcc
	v_rsq_f32_e32 v51, v8
	v_add_u32_e32 v8, v95, v84
	v_lshl_add_u64 v[92:93], v[8:9], 1, s[8:9]
	v_and_b32_e32 v65, 0xffff0000, v65
	v_mul_f32_e32 v8, 0x45800000, v51
	v_cndmask_b32_e32 v94, v51, v8, vcc
	v_pk_mul_f32 v[72:73], v[72:73], v[94:95] op_sel_hi:[1,0]
	v_cmp_gt_u32_e32 vcc, s14, v99
	s_waitcnt vmcnt(4)
	v_pk_fma_f32 v[42:43], v[42:43], v[72:73], v[46:47]
	v_pk_mul_f32 v[58:59], v[58:59], v[94:95] op_sel_hi:[1,0]
	s_waitcnt vmcnt(0)
	v_pk_fma_f32 v[42:43], v[50:51], v[74:75], v[42:43] op_sel_hi:[0,1,1]
	v_pk_mul_f32 v[38:39], v[38:39], v[42:43]
	s_nop 0
	v_cvt_pk_bf16_f32 v8, v38, v39
	v_pk_mul_f32 v[38:39], v[62:63], v[94:95] op_sel_hi:[1,0]
	v_pk_mul_f32 v[62:63], v[66:67], v[94:95] op_sel_hi:[1,0]
	v_pk_fma_f32 v[38:39], v[44:45], v[38:39], v[48:49]
	v_lshlrev_b32_e32 v48, 16, v56
	v_pk_fma_f32 v[38:39], v[50:51], v[64:65], v[38:39] op_sel_hi:[0,1,1]
	v_pk_mul_f32 v[38:39], v[40:41], v[38:39]
	v_and_b32_e32 v49, 0xffff0000, v56
	v_cvt_pk_bf16_f32 v38, v38, v39
	v_cndmask_b32_e64 v39, v38, 0, vcc
	v_cndmask_b32_e64 v38, v8, 0, vcc
	global_store_dwordx2 v[92:93], v[38:39], off
	s_nop 0
	v_lshlrev_b32_e32 v56, 16, v57
	v_and_b32_e32 v57, 0xffff0000, v57
	v_add_u32_e32 v8, v95, v85
	v_lshl_add_u64 v[46:47], v[8:9], 1, s[8:9]
	s_nop 1
	v_mov_b32_e32 v38, v174
	v_mov_b32_e32 v39, v175
	v_mov_b32_e32 v40, v176
	v_mov_b32_e32 v41, v177
	v_mov_b32_e32 v42, v186
	v_mov_b32_e32 v43, v187
	v_mov_b32_e32 v44, v188
	v_mov_b32_e32 v45, v189
	v_pk_fma_f32 v[38:39], v[58:59], v[38:39], v[42:43]
	v_pk_fma_f32 v[40:41], v[62:63], v[40:41], v[44:45]
	v_pk_fma_f32 v[38:39], v[50:51], v[48:49], v[38:39] op_sel_hi:[0,1,1]
	v_pk_fma_f32 v[40:41], v[50:51], v[56:57], v[40:41] op_sel_hi:[0,1,1]
	v_pk_mul_f32 v[34:35], v[34:35], v[38:39]
	v_pk_mul_f32 v[36:37], v[36:37], v[40:41]
	v_cvt_pk_bf16_f32 v8, v34, v35
	v_cvt_pk_bf16_f32 v34, v36, v37
	v_cndmask_b32_e64 v35, v34, 0, vcc
	v_cndmask_b32_e64 v34, v8, 0, vcc
	global_store_dwordx2 v[46:47], v[34:35], off
	s_nop 0
	v_lshlrev_b32_e32 v44, 16, v54
	v_and_b32_e32 v45, 0xffff0000, v54
	v_lshlrev_b32_e32 v46, 16, v55
	v_and_b32_e32 v47, 0xffff0000, v55
	v_pk_mul_f32 v[48:49], v[60:61], v[94:95] op_sel_hi:[1,0]
	v_pk_mul_f32 v[54:55], v[68:69], v[94:95] op_sel_hi:[1,0]
	v_add_u32_e32 v8, v95, v131
	v_lshl_add_u64 v[42:43], v[8:9], 1, s[8:9]
	s_nop 1
	v_mov_b32_e32 v34, v178
	v_mov_b32_e32 v35, v179
	v_mov_b32_e32 v36, v180
	v_mov_b32_e32 v37, v181
	v_mov_b32_e32 v38, v190
	v_mov_b32_e32 v39, v191
	v_mov_b32_e32 v40, v192
	v_mov_b32_e32 v41, v193
	v_pk_fma_f32 v[34:35], v[48:49], v[34:35], v[38:39]
	v_pk_fma_f32 v[36:37], v[54:55], v[36:37], v[40:41]
	v_pk_fma_f32 v[34:35], v[50:51], v[44:45], v[34:35] op_sel_hi:[0,1,1]
	v_pk_fma_f32 v[36:37], v[50:51], v[46:47], v[36:37] op_sel_hi:[0,1,1]
	v_pk_mul_f32 v[30:31], v[30:31], v[34:35]
	v_pk_mul_f32 v[32:33], v[32:33], v[36:37]
	v_cvt_pk_bf16_f32 v8, v30, v31
	v_cvt_pk_bf16_f32 v30, v32, v33
	v_cndmask_b32_e64 v31, v30, 0, vcc
	v_cndmask_b32_e64 v30, v8, 0, vcc
	global_store_dwordx2 v[42:43], v[30:31], off
	s_nop 0
	v_pk_mul_f32 v[42:43], v[76:77], v[94:95] op_sel_hi:[1,0]
	v_pk_mul_f32 v[44:45], v[70:71], v[94:95] op_sel_hi:[1,0]
	v_lshlrev_b32_e32 v38, 16, v52
	v_and_b32_e32 v39, 0xffff0000, v52
	v_lshlrev_b32_e32 v40, 16, v53
	v_and_b32_e32 v41, 0xffff0000, v53
	v_add_u32_e32 v8, v95, v132
	s_nop 1
	v_mov_b32_e32 v30, v182
	v_mov_b32_e32 v31, v183
	v_mov_b32_e32 v32, v184
	v_mov_b32_e32 v33, v185
	v_mov_b32_e32 v34, v194
	v_mov_b32_e32 v35, v195
	v_mov_b32_e32 v36, v196
	v_mov_b32_e32 v37, v197
	v_pk_fma_f32 v[30:31], v[42:43], v[30:31], v[34:35]
	v_pk_fma_f32 v[32:33], v[44:45], v[32:33], v[36:37]
	v_pk_fma_f32 v[30:31], v[50:51], v[38:39], v[30:31] op_sel_hi:[0,1,1]
	v_pk_fma_f32 v[32:33], v[50:51], v[40:41], v[32:33] op_sel_hi:[0,1,1]
; __device__ __forceinline__ float bf2f(bf16_t h) { return __uint_as_float(((unsigned)h) << 16); }
;     ...
;         const unsigned row = rb2 + mi * 16;
;         const unsigned pr = row % (unsigned)LP;
;         if constexpr (EPI == EPI_LG) {
;           const unsigned hh = (unsigned)(n0 + wn * 64) >> 6;
;           const unsigned bb = row / (unsigned)LP;
;           const bf16_t* yb = (bb < 2u) ? (e.y01 + (size_t)bb * LP * D) : (e.y23 + (size_t)(bb - 2u) * LP * D);
;           float yv[4][4], vv[4][4];
;           float s1 = 0.f;
; #pragma unroll
;           for (int ni = 0; ni < 4; ni++) {
;             const unsigned col = cb2 + ni * 16;
;             const uint2 yu = *(const uint2*)(yb + (size_t)pr * D + col);
;             const uint2 vu = *(const uint2*)(e.c0 + (row * (unsigned)RKLD + 2048 + col));
;             const float m_ = e.mu[row * 64u + hh * 4u + ni];
;             yv[ni][0] = bf2f((bf16_t)(yu.x & 0xffff)) + m_; yv[ni][1] = bf2f((bf16_t)(yu.x >> 16)) + m_;
;             yv[ni][2] = bf2f((bf16_t)(yu.y & 0xffff)) + m_; yv[ni][3] = bf2f((bf16_t)(yu.y >> 16)) + m_;
;             vv[ni][0] = bf2f((bf16_t)(vu.x & 0xffff)); vv[ni][1] = bf2f((bf16_t)(vu.x >> 16));
;             vv[ni][2] = bf2f((bf16_t)(vu.y & 0xffff)); vv[ni][3] = bf2f((bf16_t)(vu.y >> 16));
;             s1 += (yv[ni][0] + yv[ni][1]) + (yv[ni][2] + yv[ni][3]);
;           }
;           const float mean = xrow16_sum(s1) * (1.f / 64.f);
;           float s2 = 0.f;
; #pragma unroll
;           for (int ni = 0; ni < 4; ni++)
; #pragma unroll
;             for (int j = 0; j < 4; j++) { yv[ni][j] -= mean; s2 += yv[ni][j] * yv[ni][j]; }
;           const float rstd = rsqrtf(xrow16_sum(s2) * (1.f / 64.f) + 64e-5f);
;           const float sb = e.sbp[row * 16u + hh];
	v_pk_mul_f32 v[26:27], v[26:27], v[30:31]
	v_pk_mul_f32 v[28:29], v[28:29], v[32:33]
	v_cvt_pk_bf16_f32 v26, v26, v27
	v_cvt_pk_bf16_f32 v27, v28, v29
	v_cndmask_b32_e64 v27, v27, 0, vcc
	v_cndmask_b32_e64 v26, v26, 0, vcc
	v_lshl_add_u64 v[28:29], v[8:9], 1, s[8:9]
	global_store_dwordx2 v[28:29], v[26:27], off
	v_or_b32_e32 v67, 48, v135
	v_mul_hi_u32 v8, v67, s24
	v_lshrrev_b32_e32 v8, 13, v8
	v_mul_u32_u24_e32 v8, 0x2080, v8
	v_sub_u32_e32 v69, v67, v8
	v_lshlrev_b32_e32 v8, 11, v69
	v_lshl_add_u64 v[26:27], v[88:89], 0, v[8:9]
	v_mul_lo_u32 v8, v67, s15
	v_add_u32_e32 v30, 0x800, v8
	v_add_u32_e32 v8, v30, v84
	v_lshl_add_u64 v[26:27], v[26:27], 0, v[90:91]
	v_lshl_add_u64 v[28:29], v[8:9], 1, s[52:53]
	global_load_dwordx2 v[44:45], v[26:27], off
	global_load_dwordx2 v[46:47], v[28:29], off
	global_load_dwordx2 v[48:49], v[26:27], off offset:32
	global_load_dwordx2 v[50:51], v[26:27], off offset:64
	v_mov_b32_e32 v29, v9
	v_lshl_add_u32 v28, v67, 6, v134
	global_load_dwordx2 v[52:53], v[26:27], off offset:96
	v_lshl_add_u64 v[26:27], v[28:29], 2, s[10:11]
	global_load_dwordx4 v[32:35], v[26:27], off
	global_load_dwordx4 v[36:39], v[82:83], off
	global_load_dwordx4 v[40:43], v[86:87], off
	v_add_u32_e32 v8, v30, v85
	v_lshl_add_u64 v[26:27], v[8:9], 1, s[52:53]
	v_add_u32_e32 v8, v30, v131
	v_lshl_add_u64 v[28:29], v[8:9], 1, s[52:53]
	v_add_u32_e32 v8, v30, v132
	v_lshl_add_u64 v[54:55], v[8:9], 1, s[52:53]
	v_lshl_add_u32 v8, v67, 4, v133
	v_lshl_add_u64 v[56:57], v[8:9], 2, s[12:13]
	global_load_dwordx2 v[58:59], v[26:27], off
	global_load_dwordx2 v[30:31], v[28:29], off
	s_nop 0
	global_load_dwordx2 v[28:29], v[54:55], off
	global_load_dword v26, v[56:57], off
	s_waitcnt vmcnt(10)
	v_lshlrev_b32_e32 v56, 16, v46
	v_lshlrev_b32_e32 v54, 16, v44
	v_and_b32_e32 v55, 0xffff0000, v44
	v_lshlrev_b32_e32 v44, 16, v45
	v_and_b32_e32 v45, 0xffff0000, v45
	s_waitcnt vmcnt(8)
	v_lshlrev_b32_e32 v62, 16, v50
	v_and_b32_e32 v63, 0xffff0000, v50
	v_lshlrev_b32_e32 v50, 16, v51
	v_and_b32_e32 v51, 0xffff0000, v51
	s_waitcnt vmcnt(7)
	v_lshlrev_b32_e32 v64, 16, v52
	v_and_b32_e32 v65, 0xffff0000, v52
	s_waitcnt vmcnt(6)
	v_mov_b32_e32 v8, v35
	v_lshlrev_b32_e32 v52, 16, v53
	v_and_b32_e32 v53, 0xffff0000, v53
	v_lshlrev_b32_e32 v60, 16, v48
	v_and_b32_e32 v61, 0xffff0000, v48
	v_lshlrev_b32_e32 v48, 16, v49
	v_and_b32_e32 v49, 0xffff0000, v49
	v_pk_add_f32 v[62:63], v[34:35], v[62:63] op_sel_hi:[0,1]
	v_pk_add_f32 v[34:35], v[34:35], v[50:51] op_sel_hi:[0,1]
	v_pk_add_f32 v[50:51], v[8:9], v[64:65] op_sel_hi:[0,1]
	v_pk_add_f32 v[52:53], v[8:9], v[52:53] op_sel_hi:[0,1]
	v_pk_add_f32 v[44:45], v[32:33], v[44:45] op_sel_hi:[0,1]
	v_pk_add_f32 v[54:55], v[32:33], v[54:55] op_sel_hi:[0,1]
	v_pk_add_f32 v[48:49], v[32:33], v[48:49] op_sel:[1,0]
	v_pk_add_f32 v[32:33], v[32:33], v[60:61] op_sel:[1,0]
	v_add_f32_e32 v8, v34, v35
	v_add_f32_e32 v27, v62, v63
	v_add_f32_e32 v60, v52, v53
	v_add_f32_e32 v61, v50, v51
	v_add_f32_e32 v64, v44, v45
	v_add_f32_e32 v65, v54, v55
	v_add_f32_e32 v66, v48, v49
	v_add_f32_e32 v68, v32, v33
	v_add_f32_e32 v8, v27, v8
	v_add_f32_e32 v27, v61, v60
	v_add_f32_e32 v60, v65, v64
	v_add_f32_e32 v61, v68, v66
	v_add_f32_e32 v60, 0, v60
	v_add_f32_e32 v60, v60, v61
	v_add_f32_e32 v8, v60, v8
	v_add_f32_e32 v8, v8, v27
	v_mov_b32_e32 v27, v8
	s_nop 1
	v_permlane16_swap_b32_e32 v8, v27
	v_add_f32_e32 v8, v8, v27
	v_mov_b32_e32 v27, v8
	s_nop 1
	v_permlane32_swap_b32_e32 v8, v27
	v_add_f32_e32 v8, v8, v27
	v_mul_f32_e32 v8, 0x3c800000, v8
	v_pk_add_f32 v[54:55], v[54:55], v[8:9] op_sel_hi:[1,0] neg_lo:[0,1] neg_hi:[0,1]
	v_pk_add_f32 v[44:45], v[44:45], v[8:9] op_sel_hi:[1,0] neg_lo:[0,1] neg_hi:[0,1]
	v_pk_add_f32 v[60:61], v[32:33], v[8:9] op_sel_hi:[1,0] neg_lo:[0,1] neg_hi:[0,1]
	v_pk_add_f32 v[48:49], v[48:49], v[8:9] op_sel_hi:[1,0] neg_lo:[0,1] neg_hi:[0,1]
	v_pk_add_f32 v[62:63], v[62:63], v[8:9] op_sel_hi:[1,0] neg_lo:[0,1] neg_hi:[0,1]
	v_pk_add_f32 v[64:65], v[34:35], v[8:9] op_sel_hi:[1,0] neg_lo:[0,1] neg_hi:[0,1]
	v_pk_add_f32 v[50:51], v[50:51], v[8:9] op_sel_hi:[1,0] neg_lo:[0,1] neg_hi:[0,1]
	v_pk_add_f32 v[52:53], v[52:53], v[8:9] op_sel_hi:[1,0] neg_lo:[0,1] neg_hi:[0,1]
	v_mul_f32_e32 v8, v55, v55
	v_pk_fma_f32 v[76:77], v[54:55], v[54:55], v[8:9] op_sel_hi:[1,1,0]
	v_mul_f32_e32 v32, v45, v45
	v_pk_fma_f32 v[76:77], v[44:45], v[44:45], v[76:77]
	v_mul_f32_e32 v34, v61, v61
	v_pk_add_f32 v[32:33], v[32:33], v[76:77] op_sel_hi:[0,1]
	v_pk_fma_f32 v[32:33], v[60:61], v[60:61], v[32:33]
	v_mul_f32_e32 v66, v49, v49
	v_pk_add_f32 v[32:33], v[34:35], v[32:33] op_sel_hi:[0,1]
	v_pk_fma_f32 v[32:33], v[48:49], v[48:49], v[32:33]
	v_mul_f32_e32 v68, v63, v63
	v_pk_add_f32 v[32:33], v[66:67], v[32:33] op_sel_hi:[0,1]
	v_pk_fma_f32 v[32:33], v[62:63], v[62:63], v[32:33]
	v_mul_f32_e32 v70, v65, v65
	v_pk_add_f32 v[32:33], v[68:69], v[32:33] op_sel_hi:[0,1]
	v_pk_fma_f32 v[32:33], v[64:65], v[64:65], v[32:33]
	v_mul_f32_e32 v72, v51, v51
	v_pk_add_f32 v[32:33], v[70:71], v[32:33] op_sel_hi:[0,1]
	v_pk_fma_f32 v[32:33], v[50:51], v[50:51], v[32:33]
	v_mul_f32_e32 v74, v53, v53
	v_pk_add_f32 v[32:33], v[72:73], v[32:33] op_sel_hi:[0,1]
	v_pk_fma_f32 v[32:33], v[52:53], v[52:53], v[32:33]
	v_lshlrev_b32_e32 v67, 10, v67
	v_pk_add_f32 v[32:33], v[74:75], v[32:33] op_sel_hi:[0,1]
	v_mov_b32_e32 v8, v32
	s_nop 1
	v_permlane16_swap_b32_e32 v32, v8
	v_add_f32_e32 v8, v32, v8
	v_mov_b32_e32 v27, v8
	s_nop 1
	v_permlane32_swap_b32_e32 v8, v27
	v_add_f32_e32 v8, v8, v27
	v_fmamk_f32 v8, v8, 0x3c800000, v206
	v_mul_f32_e32 v27, 0x4b800000, v8
	v_cmp_gt_f32_e32 vcc, s5, v8
	v_and_b32_e32 v57, 0xffff0000, v46
	v_lshlrev_b32_e32 v46, 16, v47
	v_cndmask_b32_e32 v8, v8, v27, vcc
	v_rsq_f32_e32 v27, v8
	v_add_u32_e32 v8, v67, v84
	v_lshl_add_u64 v[32:33], v[8:9], 1, s[8:9]
	v_and_b32_e32 v47, 0xffff0000, v47
	v_mul_f32_e32 v8, 0x45800000, v27
	v_cndmask_b32_e32 v66, v27, v8, vcc
	v_pk_mul_f32 v[34:35], v[54:55], v[66:67] op_sel_hi:[1,0]
	v_cmp_gt_u32_e32 vcc, s14, v69
	s_waitcnt vmcnt(4)
;     ...
;           for (int ni = 0; ni < 4; ni++) {
;             const unsigned col = cb2 + ni * 16;
;             const float4 lw = *(const float4*)(e.lnw + col), lb = *(const float4*)(e.lnb + col);
;             const f32x4 a = acc[mi][ni];
;             uint2 o;
;             o.x = pack2(a[0] * (yv[ni][0] * rstd * lw.x + lb.x + sb * vv[ni][0]), a[1] * (yv[ni][1] * rstd * lw.y + lb.y + sb * vv[ni][1]));
;             o.y = pack2(a[2] * (yv[ni][2] * rstd * lw.z + lb.z + sb * vv[ni][2]), a[3] * (yv[ni][3] * rstd * lw.w + lb.w + sb * vv[ni][3]));
;             if (pr < PADR) { o.x = 0u; o.y = 0u; }
;             *(uint2*)(e.b0 + (row * (unsigned)D + col)) = o;
	v_pk_fma_f32 v[34:35], v[36:37], v[34:35], v[40:41]
	s_waitcnt vmcnt(3)
	v_lshlrev_b32_e32 v40, 16, v59
	s_waitcnt vmcnt(0)
	v_pk_fma_f32 v[34:35], v[26:27], v[56:57], v[34:35] op_sel_hi:[0,1,1]
	v_pk_mul_f32 v[22:23], v[22:23], v[34:35]
	v_and_b32_e32 v41, 0xffff0000, v59
	v_cvt_pk_bf16_f32 v8, v22, v23
	v_pk_mul_f32 v[22:23], v[44:45], v[66:67] op_sel_hi:[1,0]
	v_pk_mul_f32 v[44:45], v[48:49], v[66:67] op_sel_hi:[1,0]
	v_pk_fma_f32 v[22:23], v[38:39], v[22:23], v[42:43]
	v_pk_mul_f32 v[42:43], v[60:61], v[66:67] op_sel_hi:[1,0]
	v_pk_fma_f32 v[22:23], v[26:27], v[46:47], v[22:23] op_sel_hi:[0,1,1]
	v_pk_mul_f32 v[22:23], v[24:25], v[22:23]
	v_lshlrev_b32_e32 v38, 16, v58
	v_cvt_pk_bf16_f32 v22, v22, v23
	v_cndmask_b32_e64 v23, v22, 0, vcc
	v_cndmask_b32_e64 v22, v8, 0, vcc
	global_store_dwordx2 v[32:33], v[22:23], off
	s_nop 0
	v_and_b32_e32 v39, 0xffff0000, v58
	v_add_u32_e32 v8, v67, v85
	v_lshl_add_u64 v[36:37], v[8:9], 1, s[8:9]
	s_nop 1
	v_mov_b32_e32 v22, v174
	v_mov_b32_e32 v23, v175
	v_mov_b32_e32 v24, v176
	v_mov_b32_e32 v25, v177
	v_mov_b32_e32 v32, v186
	v_mov_b32_e32 v33, v187
	v_mov_b32_e32 v34, v188
	v_mov_b32_e32 v35, v189
	v_pk_fma_f32 v[22:23], v[42:43], v[22:23], v[32:33]
	v_pk_fma_f32 v[24:25], v[44:45], v[24:25], v[34:35]
	v_pk_fma_f32 v[22:23], v[26:27], v[38:39], v[22:23] op_sel_hi:[0,1,1]
	v_pk_fma_f32 v[24:25], v[26:27], v[40:41], v[24:25] op_sel_hi:[0,1,1]
	v_pk_mul_f32 v[18:19], v[18:19], v[22:23]
	v_pk_mul_f32 v[20:21], v[20:21], v[24:25]
	v_cvt_pk_bf16_f32 v8, v18, v19
	v_cvt_pk_bf16_f32 v18, v20, v21
	v_cndmask_b32_e64 v19, v18, 0, vcc
	v_cndmask_b32_e64 v18, v8, 0, vcc
	global_store_dwordx2 v[36:37], v[18:19], off
	s_nop 0
	v_pk_mul_f32 v[36:37], v[62:63], v[66:67] op_sel_hi:[1,0]
	v_pk_mul_f32 v[38:39], v[64:65], v[66:67] op_sel_hi:[1,0]
	v_lshlrev_b32_e32 v34, 16, v30
	v_and_b32_e32 v35, 0xffff0000, v30
	v_lshlrev_b32_e32 v30, 16, v31
	v_and_b32_e32 v31, 0xffff0000, v31
	v_add_u32_e32 v8, v67, v131
	v_lshl_add_u64 v[32:33], v[8:9], 1, s[8:9]
	s_nop 1
	v_mov_b32_e32 v18, v178
	v_mov_b32_e32 v19, v179
	v_mov_b32_e32 v20, v180
	v_mov_b32_e32 v21, v181
	v_mov_b32_e32 v22, v190
	v_mov_b32_e32 v23, v191
	v_mov_b32_e32 v24, v192
	v_mov_b32_e32 v25, v193
	v_pk_fma_f32 v[18:19], v[36:37], v[18:19], v[22:23]
	v_pk_fma_f32 v[20:21], v[38:39], v[20:21], v[24:25]
	v_pk_fma_f32 v[18:19], v[26:27], v[34:35], v[18:19] op_sel_hi:[0,1,1]
	v_pk_fma_f32 v[20:21], v[26:27], v[30:31], v[20:21] op_sel_hi:[0,1,1]
	v_pk_mul_f32 v[14:15], v[14:15], v[18:19]
	v_pk_mul_f32 v[16:17], v[16:17], v[20:21]
	v_cvt_pk_bf16_f32 v8, v14, v15
	v_cvt_pk_bf16_f32 v14, v16, v17
	v_cndmask_b32_e64 v15, v14, 0, vcc
	v_cndmask_b32_e64 v14, v8, 0, vcc
	global_store_dwordx2 v[32:33], v[14:15], off
	s_nop 0
	v_lshlrev_b32_e32 v22, 16, v28
	v_and_b32_e32 v23, 0xffff0000, v28
	v_lshlrev_b32_e32 v24, 16, v29
	v_and_b32_e32 v25, 0xffff0000, v29
	v_pk_mul_f32 v[28:29], v[50:51], v[66:67] op_sel_hi:[1,0]
	v_pk_mul_f32 v[30:31], v[52:53], v[66:67] op_sel_hi:[1,0]
	v_add_u32_e32 v8, v67, v132
	s_nop 1
	v_mov_b32_e32 v14, v182
	v_mov_b32_e32 v15, v183
	v_mov_b32_e32 v16, v184
	v_mov_b32_e32 v17, v185
	v_mov_b32_e32 v18, v194
	v_mov_b32_e32 v19, v195
	v_mov_b32_e32 v20, v196
	v_mov_b32_e32 v21, v197
	v_pk_fma_f32 v[14:15], v[28:29], v[14:15], v[18:19]
	v_pk_fma_f32 v[16:17], v[30:31], v[16:17], v[20:21]
	v_pk_fma_f32 v[14:15], v[26:27], v[22:23], v[14:15] op_sel_hi:[0,1,1]
	v_pk_fma_f32 v[16:17], v[26:27], v[24:25], v[16:17] op_sel_hi:[0,1,1]
	v_pk_mul_f32 v[10:11], v[10:11], v[14:15]
	v_pk_mul_f32 v[12:13], v[12:13], v[16:17]
	v_cvt_pk_bf16_f32 v10, v10, v11
	v_cvt_pk_bf16_f32 v11, v12, v13
	v_cndmask_b32_e64 v11, v11, 0, vcc
	v_cndmask_b32_e64 v10, v10, 0, vcc
	v_lshl_add_u64 v[12:13], v[8:9], 1, s[8:9]
	global_store_dwordx2 v[12:13], v[10:11], off
	s_add_i32 s4, s4, 1
	s_addk_i32 s2, 0x200
	s_mov_b64 s[0:1], 0

; __device__ __forceinline__ float bf2f(bf16_t h) { return __uint_as_float(((unsigned)h) << 16); }
; __device__ __forceinline__ void hyb_prep_phase(const Params& p, float* sm, int bid, int nb) {
;     ...
;     for (int it = bid * 4 + wave; it < NB * 8 * 65; it += nb * 4) {
;       const int bh = it / 65, seg = it - bh * 65;
;       const int b = bh >> 3, h = bh & 7;
;       float mq = 0.f, mk = 0.f;
; #pragma unroll 4
;       for (int g8 = 0; g8 < 16; g8++) {
;         const size_t row = (size_t)b * LP + seg * 128 + g8 * 8 + (lane >> 3);
;         const uint4 uq = *(const uint4*)(z + row * ZLD + h * 64 + (lane & 7) * 8);
;         const uint4 uk = *(const uint4*)(z + row * ZLD + 512 + h * 64 + (lane & 7) * 8);
;         const unsigned aq[4] = {uq.x, uq.y, uq.z, uq.w}, ak[4] = {uk.x, uk.y, uk.z, uk.w};
;         float sq = 0.f, sk = 0.f;
; #pragma unroll
;         for (int e = 0; e < 4; e++) {
;           const float q0 = bf2f((bf16_t)(aq[e] & 0xffff)), q1 = bf2f((bf16_t)(aq[e] >> 16));
;           const float k0 = bf2f((bf16_t)(ak[e] & 0xffff)), k1 = bf2f((bf16_t)(ak[e] >> 16));
;           sq += q0 * q0 + q1 * q1; sk += k0 * k0 + k1 * k1;
;         }
;         mq = fmaxf(mq, dpp_sum8(sq)); mk = fmaxf(mk, dpp_sum8(sk));
;       }
.LBB0_2169:
	v_add_co_u32_e32 v18, vcc, 0xb600000, v16
	s_nop 1
	v_addc_co_u32_e32 v19, vcc, 0, v17, vcc
	global_load_dwordx4 v[84:87], v[18:19], off
	global_load_dwordx4 v[88:91], v[18:19], off offset:1024
	v_add_co_u32_e32 v18, vcc, 0xe000, v18
	s_nop 1
	v_addc_co_u32_e32 v19, vcc, 0, v19, vcc
	global_load_dwordx4 v[92:95], v[18:19], off
	global_load_dwordx4 v[96:99], v[18:19], off offset:1024
	v_add_co_u32_e32 v18, vcc, 0xe000, v18
	s_nop 1
	v_addc_co_u32_e32 v19, vcc, 0, v19, vcc
	global_load_dwordx4 v[100:103], v[18:19], off
	global_load_dwordx4 v[104:107], v[18:19], off offset:1024
	v_add_co_u32_e32 v18, vcc, 0xe000, v18
	s_nop 1
	v_addc_co_u32_e32 v19, vcc, 0, v19, vcc
	global_load_dwordx4 v[108:111], v[18:19], off
	global_load_dwordx4 v[112:115], v[18:19], off offset:1024
	v_add_co_u32_e32 v18, vcc, 0xe000, v18
	s_nop 1
	v_addc_co_u32_e32 v19, vcc, 0, v19, vcc
	global_load_dwordx4 v[116:119], v[18:19], off
	global_load_dwordx4 v[120:123], v[18:19], off offset:1024
	v_add_co_u32_e32 v18, vcc, 0xe000, v18
	s_nop 1
	v_addc_co_u32_e32 v19, vcc, 0, v19, vcc
	global_load_dwordx4 v[124:127], v[18:19], off
	global_load_dwordx4 v[128:131], v[18:19], off offset:1024
	v_add_co_u32_e32 v18, vcc, 0xe000, v18
	s_nop 1
	v_addc_co_u32_e32 v19, vcc, 0, v19, vcc
	global_load_dwordx4 v[132:135], v[18:19], off
	global_load_dwordx4 v[136:139], v[18:19], off offset:1024
	v_add_co_u32_e32 v18, vcc, 0xe000, v18
	s_nop 1
	v_addc_co_u32_e32 v19, vcc, 0, v19, vcc
	global_load_dwordx4 v[140:143], v[18:19], off
	global_load_dwordx4 v[144:147], v[18:19], off offset:1024
	v_add_co_u32_e32 v18, vcc, 0xe000, v18
	s_nop 1
	v_addc_co_u32_e32 v19, vcc, 0, v19, vcc
	s_waitcnt vmcnt(0)
	v_lshlrev_b32_e32 v33, 16, v85
	v_lshlrev_b32_e32 v32, 16, v84
	v_and_b32_e32 v85, 0xffff0000, v85
	v_and_b32_e32 v84, 0xffff0000, v84
	v_pk_mul_f32 v[84:85], v[84:85], v[84:85]
	v_lshlrev_b32_e32 v35, 16, v87
	v_pk_fma_f32 v[84:85], v[32:33], v[32:33], v[84:85]
	v_lshlrev_b32_e32 v34, 16, v86
	v_and_b32_e32 v87, 0xffff0000, v87
	v_and_b32_e32 v86, 0xffff0000, v86
	v_pk_mul_f32 v[86:87], v[86:87], v[86:87]
	v_add_f32_e32 v84, v84, v85
	v_pk_fma_f32 v[86:87], v[34:35], v[34:35], v[86:87]
	s_nop 0
	v_add_f32_e32 v84, v84, v86
	v_add_f32_e32 v28, v84, v87
	v_lshlrev_b32_e32 v33, 16, v89
	v_lshlrev_b32_e32 v32, 16, v88
	v_and_b32_e32 v89, 0xffff0000, v89
	v_and_b32_e32 v88, 0xffff0000, v88
	v_pk_mul_f32 v[88:89], v[88:89], v[88:89]
	v_lshlrev_b32_e32 v35, 16, v91
	v_pk_fma_f32 v[88:89], v[32:33], v[32:33], v[88:89]
	v_lshlrev_b32_e32 v34, 16, v90
	v_and_b32_e32 v91, 0xffff0000, v91
	v_and_b32_e32 v90, 0xffff0000, v90
	v_pk_mul_f32 v[90:91], v[90:91], v[90:91]
	v_add_f32_e32 v88, v88, v89
	v_pk_fma_f32 v[90:91], v[34:35], v[34:35], v[90:91]
	s_nop 0
	v_add_f32_e32 v88, v88, v90
	v_add_f32_e32 v29, v88, v91
	s_nop 0
	v_add_f32_dpp v28, v28, v28 quad_perm:[1,0,3,2] row_mask:0xf bank_mask:0xf bound_ctrl:1
	v_add_f32_dpp v29, v29, v29 quad_perm:[1,0,3,2] row_mask:0xf bank_mask:0xf bound_ctrl:1
	s_nop 0
	v_add_f32_dpp v28, v28, v28 quad_perm:[2,3,0,1] row_mask:0xf bank_mask:0xf bound_ctrl:1
	v_add_f32_dpp v29, v29, v29 quad_perm:[2,3,0,1] row_mask:0xf bank_mask:0xf bound_ctrl:1
	s_nop 0
	v_add_f32_dpp v28, v28, v28 row_half_mirror row_mask:0xf bank_mask:0xf bound_ctrl:1
	v_add_f32_dpp v29, v29, v29 row_half_mirror row_mask:0xf bank_mask:0xf bound_ctrl:1
	v_max_f32_e32 v27, v27, v28
	v_max_f32_e32 v26, v26, v29
	v_lshlrev_b32_e32 v33, 16, v93
	v_lshlrev_b32_e32 v32, 16, v92
	v_and_b32_e32 v93, 0xffff0000, v93
	v_and_b32_e32 v92, 0xffff0000, v92
	v_pk_mul_f32 v[92:93], v[92:93], v[92:93]
	v_lshlrev_b32_e32 v35, 16, v95
	v_pk_fma_f32 v[92:93], v[32:33], v[32:33], v[92:93]
	v_lshlrev_b32_e32 v34, 16, v94
	v_and_b32_e32 v95, 0xffff0000, v95
	v_and_b32_e32 v94, 0xffff0000, v94
	v_pk_mul_f32 v[94:95], v[94:95], v[94:95]
	v_add_f32_e32 v92, v92, v93
	v_pk_fma_f32 v[94:95], v[34:35], v[34:35], v[94:95]
	s_nop 0
	v_add_f32_e32 v92, v92, v94
	v_add_f32_e32 v28, v92, v95
	v_lshlrev_b32_e32 v33, 16, v97
	v_lshlrev_b32_e32 v32, 16, v96
	v_and_b32_e32 v97, 0xffff0000, v97
	v_and_b32_e32 v96, 0xffff0000, v96
	v_pk_mul_f32 v[96:97], v[96:97], v[96:97]
	v_lshlrev_b32_e32 v35, 16, v99
	v_pk_fma_f32 v[96:97], v[32:33], v[32:33], v[96:97]
	v_lshlrev_b32_e32 v34, 16, v98
	v_and_b32_e32 v99, 0xffff0000, v99
	v_and_b32_e32 v98, 0xffff0000, v98
	v_pk_mul_f32 v[98:99], v[98:99], v[98:99]
	v_add_f32_e32 v96, v96, v97
	v_pk_fma_f32 v[98:99], v[34:35], v[34:35], v[98:99]
	s_nop 0
	v_add_f32_e32 v96, v96, v98
	v_add_f32_e32 v29, v96, v99
	s_nop 0
	v_add_f32_dpp v28, v28, v28 quad_perm:[1,0,3,2] row_mask:0xf bank_mask:0xf bound_ctrl:1
	v_add_f32_dpp v29, v29, v29 quad_perm:[1,0,3,2] row_mask:0xf bank_mask:0xf bound_ctrl:1
	s_nop 0
	v_add_f32_dpp v28, v28, v28 quad_perm:[2,3,0,1] row_mask:0xf bank_mask:0xf bound_ctrl:1
	v_add_f32_dpp v29, v29, v29 quad_perm:[2,3,0,1] row_mask:0xf bank_mask:0xf bound_ctrl:1
	s_nop 0
	v_add_f32_dpp v28, v28, v28 row_half_mirror row_mask:0xf bank_mask:0xf bound_ctrl:1
	v_add_f32_dpp v29, v29, v29 row_half_mirror row_mask:0xf bank_mask:0xf bound_ctrl:1
	v_max_f32_e32 v27, v27, v28
	v_max_f32_e32 v26, v26, v29
	v_lshlrev_b32_e32 v33, 16, v101
	v_lshlrev_b32_e32 v32, 16, v100
	v_and_b32_e32 v101, 0xffff0000, v101
	v_and_b32_e32 v100, 0xffff0000, v100
	v_pk_mul_f32 v[100:101], v[100:101], v[100:101]
	v_lshlrev_b32_e32 v35, 16, v103
	v_pk_fma_f32 v[100:101], v[32:33], v[32:33], v[100:101]
	v_lshlrev_b32_e32 v34, 16, v102
	v_and_b32_e32 v103, 0xffff0000, v103
	v_and_b32_e32 v102, 0xffff0000, v102
	v_pk_mul_f32 v[102:103], v[102:103], v[102:103]
	v_add_f32_e32 v100, v100, v101
; __device__ __forceinline__ float bf2f(bf16_t h) { return __uint_as_float(((unsigned)h) << 16); }
; __device__ __forceinline__ void hyb_prep_phase(const Params& p, float* sm, int bid, int nb) {
;     ...
; #pragma unroll 4
;       for (int g8 = 0; g8 < 16; g8++) {
;         const size_t row = (size_t)b * LP + seg * 128 + g8 * 8 + (lane >> 3);
;         const uint4 uq = *(const uint4*)(z + row * ZLD + h * 64 + (lane & 7) * 8);
;         const uint4 uk = *(const uint4*)(z + row * ZLD + 512 + h * 64 + (lane & 7) * 8);
;         const unsigned aq[4] = {uq.x, uq.y, uq.z, uq.w}, ak[4] = {uk.x, uk.y, uk.z, uk.w};
;         float sq = 0.f, sk = 0.f;
; #pragma unroll
;         for (int e = 0; e < 4; e++) {
;           const float q0 = bf2f((bf16_t)(aq[e] & 0xffff)), q1 = bf2f((bf16_t)(aq[e] >> 16));
;           const float k0 = bf2f((bf16_t)(ak[e] & 0xffff)), k1 = bf2f((bf16_t)(ak[e] >> 16));
;           sq += q0 * q0 + q1 * q1; sk += k0 * k0 + k1 * k1;
;         }
;         mq = fmaxf(mq, dpp_sum8(sq)); mk = fmaxf(mk, dpp_sum8(sk));
	v_pk_fma_f32 v[102:103], v[34:35], v[34:35], v[102:103]
	s_nop 0
	v_add_f32_e32 v100, v100, v102
	v_add_f32_e32 v28, v100, v103
	v_lshlrev_b32_e32 v33, 16, v105
	v_lshlrev_b32_e32 v32, 16, v104
	v_and_b32_e32 v105, 0xffff0000, v105
	v_and_b32_e32 v104, 0xffff0000, v104
	v_pk_mul_f32 v[104:105], v[104:105], v[104:105]
	v_lshlrev_b32_e32 v35, 16, v107
	v_pk_fma_f32 v[104:105], v[32:33], v[32:33], v[104:105]
	v_lshlrev_b32_e32 v34, 16, v106
	v_and_b32_e32 v107, 0xffff0000, v107
	v_and_b32_e32 v106, 0xffff0000, v106
	v_pk_mul_f32 v[106:107], v[106:107], v[106:107]
	v_add_f32_e32 v104, v104, v105
	v_pk_fma_f32 v[106:107], v[34:35], v[34:35], v[106:107]
	s_nop 0
	v_add_f32_e32 v104, v104, v106
	v_add_f32_e32 v29, v104, v107
	s_nop 0
	v_add_f32_dpp v28, v28, v28 quad_perm:[1,0,3,2] row_mask:0xf bank_mask:0xf bound_ctrl:1
	v_add_f32_dpp v29, v29, v29 quad_perm:[1,0,3,2] row_mask:0xf bank_mask:0xf bound_ctrl:1
	s_nop 0
	v_add_f32_dpp v28, v28, v28 quad_perm:[2,3,0,1] row_mask:0xf bank_mask:0xf bound_ctrl:1
	v_add_f32_dpp v29, v29, v29 quad_perm:[2,3,0,1] row_mask:0xf bank_mask:0xf bound_ctrl:1
	s_nop 0
	v_add_f32_dpp v28, v28, v28 row_half_mirror row_mask:0xf bank_mask:0xf bound_ctrl:1
	v_add_f32_dpp v29, v29, v29 row_half_mirror row_mask:0xf bank_mask:0xf bound_ctrl:1
	v_max_f32_e32 v27, v27, v28
	v_max_f32_e32 v26, v26, v29
	v_lshlrev_b32_e32 v33, 16, v109
	v_lshlrev_b32_e32 v32, 16, v108
	v_and_b32_e32 v109, 0xffff0000, v109
	v_and_b32_e32 v108, 0xffff0000, v108
	v_pk_mul_f32 v[108:109], v[108:109], v[108:109]
	v_lshlrev_b32_e32 v35, 16, v111
	v_pk_fma_f32 v[108:109], v[32:33], v[32:33], v[108:109]
	v_lshlrev_b32_e32 v34, 16, v110
	v_and_b32_e32 v111, 0xffff0000, v111
	v_and_b32_e32 v110, 0xffff0000, v110
	v_pk_mul_f32 v[110:111], v[110:111], v[110:111]
	v_add_f32_e32 v108, v108, v109
	v_pk_fma_f32 v[110:111], v[34:35], v[34:35], v[110:111]
	s_nop 0
	v_add_f32_e32 v108, v108, v110
	v_add_f32_e32 v28, v108, v111
	v_lshlrev_b32_e32 v33, 16, v113
	v_lshlrev_b32_e32 v32, 16, v112
	v_and_b32_e32 v113, 0xffff0000, v113
	v_and_b32_e32 v112, 0xffff0000, v112
	v_pk_mul_f32 v[112:113], v[112:113], v[112:113]
	v_lshlrev_b32_e32 v35, 16, v115
	v_pk_fma_f32 v[112:113], v[32:33], v[32:33], v[112:113]
	v_lshlrev_b32_e32 v34, 16, v114
	v_and_b32_e32 v115, 0xffff0000, v115
	v_and_b32_e32 v114, 0xffff0000, v114
	v_pk_mul_f32 v[114:115], v[114:115], v[114:115]
	v_add_f32_e32 v112, v112, v113
	v_pk_fma_f32 v[114:115], v[34:35], v[34:35], v[114:115]
	s_nop 0
	v_add_f32_e32 v112, v112, v114
	v_add_f32_e32 v29, v112, v115
	s_nop 0
	v_add_f32_dpp v28, v28, v28 quad_perm:[1,0,3,2] row_mask:0xf bank_mask:0xf bound_ctrl:1
	v_add_f32_dpp v29, v29, v29 quad_perm:[1,0,3,2] row_mask:0xf bank_mask:0xf bound_ctrl:1
	s_nop 0
	v_add_f32_dpp v28, v28, v28 quad_perm:[2,3,0,1] row_mask:0xf bank_mask:0xf bound_ctrl:1
	v_add_f32_dpp v29, v29, v29 quad_perm:[2,3,0,1] row_mask:0xf bank_mask:0xf bound_ctrl:1
	s_nop 0
	v_add_f32_dpp v28, v28, v28 row_half_mirror row_mask:0xf bank_mask:0xf bound_ctrl:1
	v_add_f32_dpp v29, v29, v29 row_half_mirror row_mask:0xf bank_mask:0xf bound_ctrl:1
	v_max_f32_e32 v27, v27, v28
	v_max_f32_e32 v26, v26, v29
	v_lshlrev_b32_e32 v33, 16, v117
	v_lshlrev_b32_e32 v32, 16, v116
	v_and_b32_e32 v117, 0xffff0000, v117
	v_and_b32_e32 v116, 0xffff0000, v116
	v_pk_mul_f32 v[116:117], v[116:117], v[116:117]
	v_lshlrev_b32_e32 v35, 16, v119
	v_pk_fma_f32 v[116:117], v[32:33], v[32:33], v[116:117]
	v_lshlrev_b32_e32 v34, 16, v118
	v_and_b32_e32 v119, 0xffff0000, v119
	v_and_b32_e32 v118, 0xffff0000, v118
	v_pk_mul_f32 v[118:119], v[118:119], v[118:119]
	v_add_f32_e32 v116, v116, v117
	v_pk_fma_f32 v[118:119], v[34:35], v[34:35], v[118:119]
	s_nop 0
	v_add_f32_e32 v116, v116, v118
	v_add_f32_e32 v28, v116, v119
	v_lshlrev_b32_e32 v33, 16, v121
	v_lshlrev_b32_e32 v32, 16, v120
	v_and_b32_e32 v121, 0xffff0000, v121
	v_and_b32_e32 v120, 0xffff0000, v120
	v_pk_mul_f32 v[120:121], v[120:121], v[120:121]
	v_lshlrev_b32_e32 v35, 16, v123
	v_pk_fma_f32 v[120:121], v[32:33], v[32:33], v[120:121]
	v_lshlrev_b32_e32 v34, 16, v122
	v_and_b32_e32 v123, 0xffff0000, v123
	v_and_b32_e32 v122, 0xffff0000, v122
	v_pk_mul_f32 v[122:123], v[122:123], v[122:123]
	v_add_f32_e32 v120, v120, v121
	v_pk_fma_f32 v[122:123], v[34:35], v[34:35], v[122:123]
	s_nop 0
	v_add_f32_e32 v120, v120, v122
	v_add_f32_e32 v29, v120, v123
	s_nop 0
	v_add_f32_dpp v28, v28, v28 quad_perm:[1,0,3,2] row_mask:0xf bank_mask:0xf bound_ctrl:1
	v_add_f32_dpp v29, v29, v29 quad_perm:[1,0,3,2] row_mask:0xf bank_mask:0xf bound_ctrl:1
	s_nop 0
	v_add_f32_dpp v28, v28, v28 quad_perm:[2,3,0,1] row_mask:0xf bank_mask:0xf bound_ctrl:1
	v_add_f32_dpp v29, v29, v29 quad_perm:[2,3,0,1] row_mask:0xf bank_mask:0xf bound_ctrl:1
	s_nop 0
	v_add_f32_dpp v28, v28, v28 row_half_mirror row_mask:0xf bank_mask:0xf bound_ctrl:1
	v_add_f32_dpp v29, v29, v29 row_half_mirror row_mask:0xf bank_mask:0xf bound_ctrl:1
	v_max_f32_e32 v27, v27, v28
	v_max_f32_e32 v26, v26, v29
	v_lshlrev_b32_e32 v33, 16, v125
	v_lshlrev_b32_e32 v32, 16, v124
	v_and_b32_e32 v125, 0xffff0000, v125
	v_and_b32_e32 v124, 0xffff0000, v124
	v_pk_mul_f32 v[124:125], v[124:125], v[124:125]
	v_lshlrev_b32_e32 v35, 16, v127
	v_pk_fma_f32 v[124:125], v[32:33], v[32:33], v[124:125]
	v_lshlrev_b32_e32 v34, 16, v126
	v_and_b32_e32 v127, 0xffff0000, v127
	v_and_b32_e32 v126, 0xffff0000, v126
	v_pk_mul_f32 v[126:127], v[126:127], v[126:127]
	v_add_f32_e32 v124, v124, v125
	v_pk_fma_f32 v[126:127], v[34:35], v[34:35], v[126:127]
	s_nop 0
	v_add_f32_e32 v124, v124, v126
	v_add_f32_e32 v28, v124, v127
	v_lshlrev_b32_e32 v33, 16, v129
	v_lshlrev_b32_e32 v32, 16, v128
; __device__ __forceinline__ float bf2f(bf16_t h) { return __uint_as_float(((unsigned)h) << 16); }
; __device__ __forceinline__ void hyb_prep_phase(const Params& p, float* sm, int bid, int nb) {
;     ...
; #pragma unroll 4
;       for (int g8 = 0; g8 < 16; g8++) {
;         const size_t row = (size_t)b * LP + seg * 128 + g8 * 8 + (lane >> 3);
;         const uint4 uq = *(const uint4*)(z + row * ZLD + h * 64 + (lane & 7) * 8);
;         const uint4 uk = *(const uint4*)(z + row * ZLD + 512 + h * 64 + (lane & 7) * 8);
;         const unsigned aq[4] = {uq.x, uq.y, uq.z, uq.w}, ak[4] = {uk.x, uk.y, uk.z, uk.w};
;         float sq = 0.f, sk = 0.f;
; #pragma unroll
;         for (int e = 0; e < 4; e++) {
;           const float q0 = bf2f((bf16_t)(aq[e] & 0xffff)), q1 = bf2f((bf16_t)(aq[e] >> 16));
;           const float k0 = bf2f((bf16_t)(ak[e] & 0xffff)), k1 = bf2f((bf16_t)(ak[e] >> 16));
;           sq += q0 * q0 + q1 * q1; sk += k0 * k0 + k1 * k1;
;         }
;         mq = fmaxf(mq, dpp_sum8(sq)); mk = fmaxf(mk, dpp_sum8(sk));
	v_and_b32_e32 v129, 0xffff0000, v129
	v_and_b32_e32 v128, 0xffff0000, v128
	v_pk_mul_f32 v[128:129], v[128:129], v[128:129]
	v_lshlrev_b32_e32 v35, 16, v131
	v_pk_fma_f32 v[128:129], v[32:33], v[32:33], v[128:129]
	v_lshlrev_b32_e32 v34, 16, v130
	v_and_b32_e32 v131, 0xffff0000, v131
	v_and_b32_e32 v130, 0xffff0000, v130
	v_pk_mul_f32 v[130:131], v[130:131], v[130:131]
	v_add_f32_e32 v128, v128, v129
	v_pk_fma_f32 v[130:131], v[34:35], v[34:35], v[130:131]
	s_nop 0
	v_add_f32_e32 v128, v128, v130
	v_add_f32_e32 v29, v128, v131
	s_nop 0
	v_add_f32_dpp v28, v28, v28 quad_perm:[1,0,3,2] row_mask:0xf bank_mask:0xf bound_ctrl:1
	v_add_f32_dpp v29, v29, v29 quad_perm:[1,0,3,2] row_mask:0xf bank_mask:0xf bound_ctrl:1
	s_nop 0
	v_add_f32_dpp v28, v28, v28 quad_perm:[2,3,0,1] row_mask:0xf bank_mask:0xf bound_ctrl:1
	v_add_f32_dpp v29, v29, v29 quad_perm:[2,3,0,1] row_mask:0xf bank_mask:0xf bound_ctrl:1
	s_nop 0
	v_add_f32_dpp v28, v28, v28 row_half_mirror row_mask:0xf bank_mask:0xf bound_ctrl:1
	v_add_f32_dpp v29, v29, v29 row_half_mirror row_mask:0xf bank_mask:0xf bound_ctrl:1
	v_max_f32_e32 v27, v27, v28
	v_max_f32_e32 v26, v26, v29
	v_lshlrev_b32_e32 v33, 16, v133
	v_lshlrev_b32_e32 v32, 16, v132
	v_and_b32_e32 v133, 0xffff0000, v133
	v_and_b32_e32 v132, 0xffff0000, v132
	v_pk_mul_f32 v[132:133], v[132:133], v[132:133]
	v_lshlrev_b32_e32 v35, 16, v135
	v_pk_fma_f32 v[132:133], v[32:33], v[32:33], v[132:133]
	v_lshlrev_b32_e32 v34, 16, v134
	v_and_b32_e32 v135, 0xffff0000, v135
	v_and_b32_e32 v134, 0xffff0000, v134
	v_pk_mul_f32 v[134:135], v[134:135], v[134:135]
	v_add_f32_e32 v132, v132, v133
	v_pk_fma_f32 v[134:135], v[34:35], v[34:35], v[134:135]
	s_nop 0
	v_add_f32_e32 v132, v132, v134
	v_add_f32_e32 v28, v132, v135
	v_lshlrev_b32_e32 v33, 16, v137
	v_lshlrev_b32_e32 v32, 16, v136
	v_and_b32_e32 v137, 0xffff0000, v137
	v_and_b32_e32 v136, 0xffff0000, v136
	v_pk_mul_f32 v[136:137], v[136:137], v[136:137]
	v_lshlrev_b32_e32 v35, 16, v139
	v_pk_fma_f32 v[136:137], v[32:33], v[32:33], v[136:137]
	v_lshlrev_b32_e32 v34, 16, v138
	v_and_b32_e32 v139, 0xffff0000, v139
	v_and_b32_e32 v138, 0xffff0000, v138
	v_pk_mul_f32 v[138:139], v[138:139], v[138:139]
	v_add_f32_e32 v136, v136, v137
	v_pk_fma_f32 v[138:139], v[34:35], v[34:35], v[138:139]
	s_nop 0
	v_add_f32_e32 v136, v136, v138
	v_add_f32_e32 v29, v136, v139
	s_nop 0
	v_add_f32_dpp v28, v28, v28 quad_perm:[1,0,3,2] row_mask:0xf bank_mask:0xf bound_ctrl:1
	v_add_f32_dpp v29, v29, v29 quad_perm:[1,0,3,2] row_mask:0xf bank_mask:0xf bound_ctrl:1
	s_nop 0
	v_add_f32_dpp v28, v28, v28 quad_perm:[2,3,0,1] row_mask:0xf bank_mask:0xf bound_ctrl:1
	v_add_f32_dpp v29, v29, v29 quad_perm:[2,3,0,1] row_mask:0xf bank_mask:0xf bound_ctrl:1
	s_nop 0
	v_add_f32_dpp v28, v28, v28 row_half_mirror row_mask:0xf bank_mask:0xf bound_ctrl:1
	v_add_f32_dpp v29, v29, v29 row_half_mirror row_mask:0xf bank_mask:0xf bound_ctrl:1
	v_max_f32_e32 v27, v27, v28
	v_max_f32_e32 v26, v26, v29
	v_lshlrev_b32_e32 v33, 16, v141
	v_lshlrev_b32_e32 v32, 16, v140
	v_and_b32_e32 v141, 0xffff0000, v141
	v_and_b32_e32 v140, 0xffff0000, v140
	v_pk_mul_f32 v[140:141], v[140:141], v[140:141]
	v_lshlrev_b32_e32 v35, 16, v143
	v_pk_fma_f32 v[140:141], v[32:33], v[32:33], v[140:141]
	v_lshlrev_b32_e32 v34, 16, v142
	v_and_b32_e32 v143, 0xffff0000, v143
	v_and_b32_e32 v142, 0xffff0000, v142
	v_pk_mul_f32 v[142:143], v[142:143], v[142:143]
	v_add_f32_e32 v140, v140, v141
	v_pk_fma_f32 v[142:143], v[34:35], v[34:35], v[142:143]
	s_nop 0
	v_add_f32_e32 v140, v140, v142
	v_add_f32_e32 v28, v140, v143
	v_lshlrev_b32_e32 v33, 16, v145
	v_lshlrev_b32_e32 v32, 16, v144
	v_and_b32_e32 v145, 0xffff0000, v145
	v_and_b32_e32 v144, 0xffff0000, v144
	v_pk_mul_f32 v[144:145], v[144:145], v[144:145]
	v_lshlrev_b32_e32 v35, 16, v147
	v_pk_fma_f32 v[144:145], v[32:33], v[32:33], v[144:145]
	v_lshlrev_b32_e32 v34, 16, v146
	v_and_b32_e32 v147, 0xffff0000, v147
	v_and_b32_e32 v146, 0xffff0000, v146
	v_pk_mul_f32 v[146:147], v[146:147], v[146:147]
	v_add_f32_e32 v144, v144, v145
	v_pk_fma_f32 v[146:147], v[34:35], v[34:35], v[146:147]
	s_nop 0
	v_add_f32_e32 v144, v144, v146
	v_add_f32_e32 v29, v144, v147
	s_nop 0
	v_add_f32_dpp v28, v28, v28 quad_perm:[1,0,3,2] row_mask:0xf bank_mask:0xf bound_ctrl:1
	v_add_f32_dpp v29, v29, v29 quad_perm:[1,0,3,2] row_mask:0xf bank_mask:0xf bound_ctrl:1
	s_nop 0
	v_add_f32_dpp v28, v28, v28 quad_perm:[2,3,0,1] row_mask:0xf bank_mask:0xf bound_ctrl:1
	v_add_f32_dpp v29, v29, v29 quad_perm:[2,3,0,1] row_mask:0xf bank_mask:0xf bound_ctrl:1
	s_nop 0
	v_add_f32_dpp v28, v28, v28 row_half_mirror row_mask:0xf bank_mask:0xf bound_ctrl:1
	v_add_f32_dpp v29, v29, v29 row_half_mirror row_mask:0xf bank_mask:0xf bound_ctrl:1
	v_max_f32_e32 v27, v27, v28
	v_max_f32_e32 v26, v26, v29
	global_load_dwordx4 v[84:87], v[18:19], off
	global_load_dwordx4 v[88:91], v[18:19], off offset:1024
	v_add_co_u32_e32 v18, vcc, 0xe000, v18
	s_nop 1
	v_addc_co_u32_e32 v19, vcc, 0, v19, vcc
	global_load_dwordx4 v[92:95], v[18:19], off
	global_load_dwordx4 v[96:99], v[18:19], off offset:1024
	v_add_co_u32_e32 v18, vcc, 0xe000, v18
	s_nop 1
	v_addc_co_u32_e32 v19, vcc, 0, v19, vcc
	global_load_dwordx4 v[100:103], v[18:19], off
	global_load_dwordx4 v[104:107], v[18:19], off offset:1024
	v_add_co_u32_e32 v18, vcc, 0xe000, v18
	s_nop 1
	v_addc_co_u32_e32 v19, vcc, 0, v19, vcc
	global_load_dwordx4 v[108:111], v[18:19], off
	global_load_dwordx4 v[112:115], v[18:19], off offset:1024
	v_add_co_u32_e32 v18, vcc, 0xe000, v18
	s_nop 1
	v_addc_co_u32_e32 v19, vcc, 0, v19, vcc
	global_load_dwordx4 v[116:119], v[18:19], off
	global_load_dwordx4 v[120:123], v[18:19], off offset:1024
	v_add_co_u32_e32 v18, vcc, 0xe000, v18
	s_nop 1
	v_addc_co_u32_e32 v19, vcc, 0, v19, vcc
	global_load_dwordx4 v[124:127], v[18:19], off
	global_load_dwordx4 v[128:131], v[18:19], off offset:1024
	v_add_co_u32_e32 v18, vcc, 0xe000, v18
	s_nop 1
	v_addc_co_u32_e32 v19, vcc, 0, v19, vcc
	global_load_dwordx4 v[132:135], v[18:19], off
	global_load_dwordx4 v[136:139], v[18:19], off offset:1024
	v_add_co_u32_e32 v18, vcc, 0xe000, v18
	s_nop 1
	v_addc_co_u32_e32 v19, vcc, 0, v19, vcc
	global_load_dwordx4 v[140:143], v[18:19], off
	global_load_dwordx4 v[144:147], v[18:19], off offset:1024
	v_add_co_u32_e32 v18, vcc, 0xe000, v18
	s_nop 1
	v_addc_co_u32_e32 v19, vcc, 0, v19, vcc
	s_waitcnt vmcnt(0)
; __device__ __forceinline__ float bf2f(bf16_t h) { return __uint_as_float(((unsigned)h) << 16); }
; __device__ __forceinline__ void hyb_prep_phase(const Params& p, float* sm, int bid, int nb) {
;     ...
; #pragma unroll 4
;       for (int g8 = 0; g8 < 16; g8++) {
;         const size_t row = (size_t)b * LP + seg * 128 + g8 * 8 + (lane >> 3);
;         const uint4 uq = *(const uint4*)(z + row * ZLD + h * 64 + (lane & 7) * 8);
;         const uint4 uk = *(const uint4*)(z + row * ZLD + 512 + h * 64 + (lane & 7) * 8);
;         const unsigned aq[4] = {uq.x, uq.y, uq.z, uq.w}, ak[4] = {uk.x, uk.y, uk.z, uk.w};
;         float sq = 0.f, sk = 0.f;
; #pragma unroll
;         for (int e = 0; e < 4; e++) {
;           const float q0 = bf2f((bf16_t)(aq[e] & 0xffff)), q1 = bf2f((bf16_t)(aq[e] >> 16));
;           const float k0 = bf2f((bf16_t)(ak[e] & 0xffff)), k1 = bf2f((bf16_t)(ak[e] >> 16));
;           sq += q0 * q0 + q1 * q1; sk += k0 * k0 + k1 * k1;
;         }
;         mq = fmaxf(mq, dpp_sum8(sq)); mk = fmaxf(mk, dpp_sum8(sk));
	v_lshlrev_b32_e32 v33, 16, v85
	v_lshlrev_b32_e32 v32, 16, v84
	v_and_b32_e32 v85, 0xffff0000, v85
	v_and_b32_e32 v84, 0xffff0000, v84
	v_pk_mul_f32 v[84:85], v[84:85], v[84:85]
	v_lshlrev_b32_e32 v35, 16, v87
	v_pk_fma_f32 v[84:85], v[32:33], v[32:33], v[84:85]
	v_lshlrev_b32_e32 v34, 16, v86
	v_and_b32_e32 v87, 0xffff0000, v87
	v_and_b32_e32 v86, 0xffff0000, v86
	v_pk_mul_f32 v[86:87], v[86:87], v[86:87]
	v_add_f32_e32 v84, v84, v85
	v_pk_fma_f32 v[86:87], v[34:35], v[34:35], v[86:87]
	s_nop 0
	v_add_f32_e32 v84, v84, v86
	v_add_f32_e32 v28, v84, v87
	v_lshlrev_b32_e32 v33, 16, v89
	v_lshlrev_b32_e32 v32, 16, v88
	v_and_b32_e32 v89, 0xffff0000, v89
	v_and_b32_e32 v88, 0xffff0000, v88
	v_pk_mul_f32 v[88:89], v[88:89], v[88:89]
	v_lshlrev_b32_e32 v35, 16, v91
	v_pk_fma_f32 v[88:89], v[32:33], v[32:33], v[88:89]
	v_lshlrev_b32_e32 v34, 16, v90
	v_and_b32_e32 v91, 0xffff0000, v91
	v_and_b32_e32 v90, 0xffff0000, v90
	v_pk_mul_f32 v[90:91], v[90:91], v[90:91]
	v_add_f32_e32 v88, v88, v89
	v_pk_fma_f32 v[90:91], v[34:35], v[34:35], v[90:91]
	s_nop 0
	v_add_f32_e32 v88, v88, v90
	v_add_f32_e32 v29, v88, v91
	s_nop 0
	v_add_f32_dpp v28, v28, v28 quad_perm:[1,0,3,2] row_mask:0xf bank_mask:0xf bound_ctrl:1
	v_add_f32_dpp v29, v29, v29 quad_perm:[1,0,3,2] row_mask:0xf bank_mask:0xf bound_ctrl:1
	s_nop 0
	v_add_f32_dpp v28, v28, v28 quad_perm:[2,3,0,1] row_mask:0xf bank_mask:0xf bound_ctrl:1
	v_add_f32_dpp v29, v29, v29 quad_perm:[2,3,0,1] row_mask:0xf bank_mask:0xf bound_ctrl:1
	s_nop 0
	v_add_f32_dpp v28, v28, v28 row_half_mirror row_mask:0xf bank_mask:0xf bound_ctrl:1
	v_add_f32_dpp v29, v29, v29 row_half_mirror row_mask:0xf bank_mask:0xf bound_ctrl:1
	v_max_f32_e32 v27, v27, v28
	v_max_f32_e32 v26, v26, v29
	v_lshlrev_b32_e32 v33, 16, v93
	v_lshlrev_b32_e32 v32, 16, v92
	v_and_b32_e32 v93, 0xffff0000, v93
	v_and_b32_e32 v92, 0xffff0000, v92
	v_pk_mul_f32 v[92:93], v[92:93], v[92:93]
	v_lshlrev_b32_e32 v35, 16, v95
	v_pk_fma_f32 v[92:93], v[32:33], v[32:33], v[92:93]
	v_lshlrev_b32_e32 v34, 16, v94
	v_and_b32_e32 v95, 0xffff0000, v95
	v_and_b32_e32 v94, 0xffff0000, v94
	v_pk_mul_f32 v[94:95], v[94:95], v[94:95]
	v_add_f32_e32 v92, v92, v93
	v_pk_fma_f32 v[94:95], v[34:35], v[34:35], v[94:95]
	s_nop 0
	v_add_f32_e32 v92, v92, v94
	v_add_f32_e32 v28, v92, v95
	v_lshlrev_b32_e32 v33, 16, v97
	v_lshlrev_b32_e32 v32, 16, v96
	v_and_b32_e32 v97, 0xffff0000, v97
	v_and_b32_e32 v96, 0xffff0000, v96
	v_pk_mul_f32 v[96:97], v[96:97], v[96:97]
	v_lshlrev_b32_e32 v35, 16, v99
	v_pk_fma_f32 v[96:97], v[32:33], v[32:33], v[96:97]
	v_lshlrev_b32_e32 v34, 16, v98
	v_and_b32_e32 v99, 0xffff0000, v99
	v_and_b32_e32 v98, 0xffff0000, v98
	v_pk_mul_f32 v[98:99], v[98:99], v[98:99]
	v_add_f32_e32 v96, v96, v97
	v_pk_fma_f32 v[98:99], v[34:35], v[34:35], v[98:99]
	s_nop 0
	v_add_f32_e32 v96, v96, v98
	v_add_f32_e32 v29, v96, v99
	s_nop 0
	v_add_f32_dpp v28, v28, v28 quad_perm:[1,0,3,2] row_mask:0xf bank_mask:0xf bound_ctrl:1
	v_add_f32_dpp v29, v29, v29 quad_perm:[1,0,3,2] row_mask:0xf bank_mask:0xf bound_ctrl:1
	s_nop 0
	v_add_f32_dpp v28, v28, v28 quad_perm:[2,3,0,1] row_mask:0xf bank_mask:0xf bound_ctrl:1
	v_add_f32_dpp v29, v29, v29 quad_perm:[2,3,0,1] row_mask:0xf bank_mask:0xf bound_ctrl:1
	s_nop 0
	v_add_f32_dpp v28, v28, v28 row_half_mirror row_mask:0xf bank_mask:0xf bound_ctrl:1
	v_add_f32_dpp v29, v29, v29 row_half_mirror row_mask:0xf bank_mask:0xf bound_ctrl:1
	v_max_f32_e32 v27, v27, v28
	v_max_f32_e32 v26, v26, v29
	v_lshlrev_b32_e32 v33, 16, v101
	v_lshlrev_b32_e32 v32, 16, v100
	v_and_b32_e32 v101, 0xffff0000, v101
	v_and_b32_e32 v100, 0xffff0000, v100
	v_pk_mul_f32 v[100:101], v[100:101], v[100:101]
	v_lshlrev_b32_e32 v35, 16, v103
	v_pk_fma_f32 v[100:101], v[32:33], v[32:33], v[100:101]
	v_lshlrev_b32_e32 v34, 16, v102
	v_and_b32_e32 v103, 0xffff0000, v103
	v_and_b32_e32 v102, 0xffff0000, v102
	v_pk_mul_f32 v[102:103], v[102:103], v[102:103]
	v_add_f32_e32 v100, v100, v101
	v_pk_fma_f32 v[102:103], v[34:35], v[34:35], v[102:103]
	s_nop 0
	v_add_f32_e32 v100, v100, v102
	v_add_f32_e32 v28, v100, v103
	v_lshlrev_b32_e32 v33, 16, v105
	v_lshlrev_b32_e32 v32, 16, v104
	v_and_b32_e32 v105, 0xffff0000, v105
	v_and_b32_e32 v104, 0xffff0000, v104
	v_pk_mul_f32 v[104:105], v[104:105], v[104:105]
	v_lshlrev_b32_e32 v35, 16, v107
	v_pk_fma_f32 v[104:105], v[32:33], v[32:33], v[104:105]
	v_lshlrev_b32_e32 v34, 16, v106
	v_and_b32_e32 v107, 0xffff0000, v107
	v_and_b32_e32 v106, 0xffff0000, v106
	v_pk_mul_f32 v[106:107], v[106:107], v[106:107]
	v_add_f32_e32 v104, v104, v105
	v_pk_fma_f32 v[106:107], v[34:35], v[34:35], v[106:107]
	s_nop 0
	v_add_f32_e32 v104, v104, v106
	v_add_f32_e32 v29, v104, v107
	s_nop 0
	v_add_f32_dpp v28, v28, v28 quad_perm:[1,0,3,2] row_mask:0xf bank_mask:0xf bound_ctrl:1
	v_add_f32_dpp v29, v29, v29 quad_perm:[1,0,3,2] row_mask:0xf bank_mask:0xf bound_ctrl:1
	s_nop 0
	v_add_f32_dpp v28, v28, v28 quad_perm:[2,3,0,1] row_mask:0xf bank_mask:0xf bound_ctrl:1
	v_add_f32_dpp v29, v29, v29 quad_perm:[2,3,0,1] row_mask:0xf bank_mask:0xf bound_ctrl:1
	s_nop 0
	v_add_f32_dpp v28, v28, v28 row_half_mirror row_mask:0xf bank_mask:0xf bound_ctrl:1
	v_add_f32_dpp v29, v29, v29 row_half_mirror row_mask:0xf bank_mask:0xf bound_ctrl:1
	v_max_f32_e32 v27, v27, v28
	v_max_f32_e32 v26, v26, v29
	v_lshlrev_b32_e32 v33, 16, v109
	v_lshlrev_b32_e32 v32, 16, v108
	v_and_b32_e32 v109, 0xffff0000, v109
	v_and_b32_e32 v108, 0xffff0000, v108
	v_pk_mul_f32 v[108:109], v[108:109], v[108:109]
	v_lshlrev_b32_e32 v35, 16, v111
	v_pk_fma_f32 v[108:109], v[32:33], v[32:33], v[108:109]
	v_lshlrev_b32_e32 v34, 16, v110
	v_and_b32_e32 v111, 0xffff0000, v111
; __device__ __forceinline__ float bf2f(bf16_t h) { return __uint_as_float(((unsigned)h) << 16); }
; __device__ __forceinline__ void hyb_prep_phase(const Params& p, float* sm, int bid, int nb) {
;     ...
; #pragma unroll 4
;       for (int g8 = 0; g8 < 16; g8++) {
;         const size_t row = (size_t)b * LP + seg * 128 + g8 * 8 + (lane >> 3);
;         const uint4 uq = *(const uint4*)(z + row * ZLD + h * 64 + (lane & 7) * 8);
;         const uint4 uk = *(const uint4*)(z + row * ZLD + 512 + h * 64 + (lane & 7) * 8);
;         const unsigned aq[4] = {uq.x, uq.y, uq.z, uq.w}, ak[4] = {uk.x, uk.y, uk.z, uk.w};
;         float sq = 0.f, sk = 0.f;
; #pragma unroll
;         for (int e = 0; e < 4; e++) {
;           const float q0 = bf2f((bf16_t)(aq[e] & 0xffff)), q1 = bf2f((bf16_t)(aq[e] >> 16));
;           const float k0 = bf2f((bf16_t)(ak[e] & 0xffff)), k1 = bf2f((bf16_t)(ak[e] >> 16));
;           sq += q0 * q0 + q1 * q1; sk += k0 * k0 + k1 * k1;
;         }
;         mq = fmaxf(mq, dpp_sum8(sq)); mk = fmaxf(mk, dpp_sum8(sk));
	v_and_b32_e32 v110, 0xffff0000, v110
	v_pk_mul_f32 v[110:111], v[110:111], v[110:111]
	v_add_f32_e32 v108, v108, v109
	v_pk_fma_f32 v[110:111], v[34:35], v[34:35], v[110:111]
	s_nop 0
	v_add_f32_e32 v108, v108, v110
	v_add_f32_e32 v28, v108, v111
	v_lshlrev_b32_e32 v33, 16, v113
	v_lshlrev_b32_e32 v32, 16, v112
	v_and_b32_e32 v113, 0xffff0000, v113
	v_and_b32_e32 v112, 0xffff0000, v112
	v_pk_mul_f32 v[112:113], v[112:113], v[112:113]
	v_lshlrev_b32_e32 v35, 16, v115
	v_pk_fma_f32 v[112:113], v[32:33], v[32:33], v[112:113]
	v_lshlrev_b32_e32 v34, 16, v114
	v_and_b32_e32 v115, 0xffff0000, v115
	v_and_b32_e32 v114, 0xffff0000, v114
	v_pk_mul_f32 v[114:115], v[114:115], v[114:115]
	v_add_f32_e32 v112, v112, v113
	v_pk_fma_f32 v[114:115], v[34:35], v[34:35], v[114:115]
	s_nop 0
	v_add_f32_e32 v112, v112, v114
	v_add_f32_e32 v29, v112, v115
	s_nop 0
	v_add_f32_dpp v28, v28, v28 quad_perm:[1,0,3,2] row_mask:0xf bank_mask:0xf bound_ctrl:1
	v_add_f32_dpp v29, v29, v29 quad_perm:[1,0,3,2] row_mask:0xf bank_mask:0xf bound_ctrl:1
	s_nop 0
	v_add_f32_dpp v28, v28, v28 quad_perm:[2,3,0,1] row_mask:0xf bank_mask:0xf bound_ctrl:1
	v_add_f32_dpp v29, v29, v29 quad_perm:[2,3,0,1] row_mask:0xf bank_mask:0xf bound_ctrl:1
	s_nop 0
	v_add_f32_dpp v28, v28, v28 row_half_mirror row_mask:0xf bank_mask:0xf bound_ctrl:1
	v_add_f32_dpp v29, v29, v29 row_half_mirror row_mask:0xf bank_mask:0xf bound_ctrl:1
	v_max_f32_e32 v27, v27, v28
	v_max_f32_e32 v26, v26, v29
	v_lshlrev_b32_e32 v33, 16, v117
	v_lshlrev_b32_e32 v32, 16, v116
	v_and_b32_e32 v117, 0xffff0000, v117
	v_and_b32_e32 v116, 0xffff0000, v116
	v_pk_mul_f32 v[116:117], v[116:117], v[116:117]
	v_lshlrev_b32_e32 v35, 16, v119
	v_pk_fma_f32 v[116:117], v[32:33], v[32:33], v[116:117]
	v_lshlrev_b32_e32 v34, 16, v118
	v_and_b32_e32 v119, 0xffff0000, v119
	v_and_b32_e32 v118, 0xffff0000, v118
	v_pk_mul_f32 v[118:119], v[118:119], v[118:119]
	v_add_f32_e32 v116, v116, v117
	v_pk_fma_f32 v[118:119], v[34:35], v[34:35], v[118:119]
	s_nop 0
	v_add_f32_e32 v116, v116, v118
	v_add_f32_e32 v28, v116, v119
	v_lshlrev_b32_e32 v33, 16, v121
	v_lshlrev_b32_e32 v32, 16, v120
	v_and_b32_e32 v121, 0xffff0000, v121
	v_and_b32_e32 v120, 0xffff0000, v120
	v_pk_mul_f32 v[120:121], v[120:121], v[120:121]
	v_lshlrev_b32_e32 v35, 16, v123
	v_pk_fma_f32 v[120:121], v[32:33], v[32:33], v[120:121]
	v_lshlrev_b32_e32 v34, 16, v122
	v_and_b32_e32 v123, 0xffff0000, v123
	v_and_b32_e32 v122, 0xffff0000, v122
	v_pk_mul_f32 v[122:123], v[122:123], v[122:123]
	v_add_f32_e32 v120, v120, v121
	v_pk_fma_f32 v[122:123], v[34:35], v[34:35], v[122:123]
	s_nop 0
	v_add_f32_e32 v120, v120, v122
	v_add_f32_e32 v29, v120, v123
	s_nop 0
	v_add_f32_dpp v28, v28, v28 quad_perm:[1,0,3,2] row_mask:0xf bank_mask:0xf bound_ctrl:1
	v_add_f32_dpp v29, v29, v29 quad_perm:[1,0,3,2] row_mask:0xf bank_mask:0xf bound_ctrl:1
	s_nop 0
	v_add_f32_dpp v28, v28, v28 quad_perm:[2,3,0,1] row_mask:0xf bank_mask:0xf bound_ctrl:1
	v_add_f32_dpp v29, v29, v29 quad_perm:[2,3,0,1] row_mask:0xf bank_mask:0xf bound_ctrl:1
	s_nop 0
	v_add_f32_dpp v28, v28, v28 row_half_mirror row_mask:0xf bank_mask:0xf bound_ctrl:1
	v_add_f32_dpp v29, v29, v29 row_half_mirror row_mask:0xf bank_mask:0xf bound_ctrl:1
	v_max_f32_e32 v27, v27, v28
	v_max_f32_e32 v26, v26, v29
	v_lshlrev_b32_e32 v33, 16, v125
	v_lshlrev_b32_e32 v32, 16, v124
	v_and_b32_e32 v125, 0xffff0000, v125
	v_and_b32_e32 v124, 0xffff0000, v124
	v_pk_mul_f32 v[124:125], v[124:125], v[124:125]
	v_lshlrev_b32_e32 v35, 16, v127
	v_pk_fma_f32 v[124:125], v[32:33], v[32:33], v[124:125]
	v_lshlrev_b32_e32 v34, 16, v126
	v_and_b32_e32 v127, 0xffff0000, v127
	v_and_b32_e32 v126, 0xffff0000, v126
	v_pk_mul_f32 v[126:127], v[126:127], v[126:127]
	v_add_f32_e32 v124, v124, v125
	v_pk_fma_f32 v[126:127], v[34:35], v[34:35], v[126:127]
	s_nop 0
	v_add_f32_e32 v124, v124, v126
	v_add_f32_e32 v28, v124, v127
	v_lshlrev_b32_e32 v33, 16, v129
	v_lshlrev_b32_e32 v32, 16, v128
	v_and_b32_e32 v129, 0xffff0000, v129
	v_and_b32_e32 v128, 0xffff0000, v128
	v_pk_mul_f32 v[128:129], v[128:129], v[128:129]
	v_lshlrev_b32_e32 v35, 16, v131
	v_pk_fma_f32 v[128:129], v[32:33], v[32:33], v[128:129]
	v_lshlrev_b32_e32 v34, 16, v130
	v_and_b32_e32 v131, 0xffff0000, v131
	v_and_b32_e32 v130, 0xffff0000, v130
	v_pk_mul_f32 v[130:131], v[130:131], v[130:131]
	v_add_f32_e32 v128, v128, v129
	v_pk_fma_f32 v[130:131], v[34:35], v[34:35], v[130:131]
	s_nop 0
	v_add_f32_e32 v128, v128, v130
	v_add_f32_e32 v29, v128, v131
	s_nop 0
	v_add_f32_dpp v28, v28, v28 quad_perm:[1,0,3,2] row_mask:0xf bank_mask:0xf bound_ctrl:1
	v_add_f32_dpp v29, v29, v29 quad_perm:[1,0,3,2] row_mask:0xf bank_mask:0xf bound_ctrl:1
	s_nop 0
	v_add_f32_dpp v28, v28, v28 quad_perm:[2,3,0,1] row_mask:0xf bank_mask:0xf bound_ctrl:1
	v_add_f32_dpp v29, v29, v29 quad_perm:[2,3,0,1] row_mask:0xf bank_mask:0xf bound_ctrl:1
	s_nop 0
	v_add_f32_dpp v28, v28, v28 row_half_mirror row_mask:0xf bank_mask:0xf bound_ctrl:1
	v_add_f32_dpp v29, v29, v29 row_half_mirror row_mask:0xf bank_mask:0xf bound_ctrl:1
	v_max_f32_e32 v27, v27, v28
	v_max_f32_e32 v26, v26, v29
	v_lshlrev_b32_e32 v33, 16, v133
	v_lshlrev_b32_e32 v32, 16, v132
	v_and_b32_e32 v133, 0xffff0000, v133
	v_and_b32_e32 v132, 0xffff0000, v132
; __device__ __forceinline__ float bf2f(bf16_t h) { return __uint_as_float(((unsigned)h) << 16); }
; __device__ __forceinline__ void hyb_prep_phase(const Params& p, float* sm, int bid, int nb) {
;     ...
;           const float q0 = bf2f((bf16_t)(aq[e] & 0xffff)), q1 = bf2f((bf16_t)(aq[e] >> 16));
;           const float k0 = bf2f((bf16_t)(ak[e] & 0xffff)), k1 = bf2f((bf16_t)(ak[e] >> 16));
;           sq += q0 * q0 + q1 * q1; sk += k0 * k0 + k1 * k1;
;         }
;         mq = fmaxf(mq, dpp_sum8(sq)); mk = fmaxf(mk, dpp_sum8(sk));
;       }
; #pragma unroll
;       for (int o = 32; o > 0; o >>= 1) { mq = fmaxf(mq, __shfl_xor(mq, o)); mk = fmaxf(mk, __shfl_xor(mk, o)); }
;       if (lane == 0) { atomicMax(&stats[bh * 2], __float_as_uint(mq)); atomicMax(&stats[bh * 2 + 1], __float_as_uint(mk)); }
	v_pk_mul_f32 v[132:133], v[132:133], v[132:133]
	v_lshlrev_b32_e32 v35, 16, v135
	v_pk_fma_f32 v[132:133], v[32:33], v[32:33], v[132:133]
	v_lshlrev_b32_e32 v34, 16, v134
	v_and_b32_e32 v135, 0xffff0000, v135
	v_and_b32_e32 v134, 0xffff0000, v134
	v_pk_mul_f32 v[134:135], v[134:135], v[134:135]
	v_add_f32_e32 v132, v132, v133
	v_pk_fma_f32 v[134:135], v[34:35], v[34:35], v[134:135]
	s_nop 0
	v_add_f32_e32 v132, v132, v134
	v_add_f32_e32 v28, v132, v135
	v_lshlrev_b32_e32 v33, 16, v137
	v_lshlrev_b32_e32 v32, 16, v136
	v_and_b32_e32 v137, 0xffff0000, v137
	v_and_b32_e32 v136, 0xffff0000, v136
	v_pk_mul_f32 v[136:137], v[136:137], v[136:137]
	v_lshlrev_b32_e32 v35, 16, v139
	v_pk_fma_f32 v[136:137], v[32:33], v[32:33], v[136:137]
	v_lshlrev_b32_e32 v34, 16, v138
	v_and_b32_e32 v139, 0xffff0000, v139
	v_and_b32_e32 v138, 0xffff0000, v138
	v_pk_mul_f32 v[138:139], v[138:139], v[138:139]
	v_add_f32_e32 v136, v136, v137
	v_pk_fma_f32 v[138:139], v[34:35], v[34:35], v[138:139]
	s_nop 0
	v_add_f32_e32 v136, v136, v138
	v_add_f32_e32 v29, v136, v139
	s_nop 0
	v_add_f32_dpp v28, v28, v28 quad_perm:[1,0,3,2] row_mask:0xf bank_mask:0xf bound_ctrl:1
	v_add_f32_dpp v29, v29, v29 quad_perm:[1,0,3,2] row_mask:0xf bank_mask:0xf bound_ctrl:1
	s_nop 0
	v_add_f32_dpp v28, v28, v28 quad_perm:[2,3,0,1] row_mask:0xf bank_mask:0xf bound_ctrl:1
	v_add_f32_dpp v29, v29, v29 quad_perm:[2,3,0,1] row_mask:0xf bank_mask:0xf bound_ctrl:1
	s_nop 0
	v_add_f32_dpp v28, v28, v28 row_half_mirror row_mask:0xf bank_mask:0xf bound_ctrl:1
	v_add_f32_dpp v29, v29, v29 row_half_mirror row_mask:0xf bank_mask:0xf bound_ctrl:1
	v_max_f32_e32 v27, v27, v28
	v_max_f32_e32 v26, v26, v29
	v_lshlrev_b32_e32 v33, 16, v141
	v_lshlrev_b32_e32 v32, 16, v140
	v_and_b32_e32 v141, 0xffff0000, v141
	v_and_b32_e32 v140, 0xffff0000, v140
	v_pk_mul_f32 v[140:141], v[140:141], v[140:141]
	v_lshlrev_b32_e32 v35, 16, v143
	v_pk_fma_f32 v[140:141], v[32:33], v[32:33], v[140:141]
	v_lshlrev_b32_e32 v34, 16, v142
	v_and_b32_e32 v143, 0xffff0000, v143
	v_and_b32_e32 v142, 0xffff0000, v142
	v_pk_mul_f32 v[142:143], v[142:143], v[142:143]
	v_add_f32_e32 v140, v140, v141
	v_pk_fma_f32 v[142:143], v[34:35], v[34:35], v[142:143]
	s_nop 0
	v_add_f32_e32 v140, v140, v142
	v_add_f32_e32 v28, v140, v143
	v_lshlrev_b32_e32 v33, 16, v145
	v_lshlrev_b32_e32 v32, 16, v144
	v_and_b32_e32 v145, 0xffff0000, v145
	v_and_b32_e32 v144, 0xffff0000, v144
	v_pk_mul_f32 v[144:145], v[144:145], v[144:145]
	v_lshlrev_b32_e32 v35, 16, v147
	v_pk_fma_f32 v[144:145], v[32:33], v[32:33], v[144:145]
	v_lshlrev_b32_e32 v34, 16, v146
	v_and_b32_e32 v147, 0xffff0000, v147
	v_and_b32_e32 v146, 0xffff0000, v146
	v_pk_mul_f32 v[146:147], v[146:147], v[146:147]
	v_add_f32_e32 v144, v144, v145
	v_pk_fma_f32 v[146:147], v[34:35], v[34:35], v[146:147]
	s_nop 0
	v_add_f32_e32 v144, v144, v146
	v_add_f32_e32 v29, v144, v147
	s_nop 0
	v_add_f32_dpp v28, v28, v28 quad_perm:[1,0,3,2] row_mask:0xf bank_mask:0xf bound_ctrl:1
	v_add_f32_dpp v29, v29, v29 quad_perm:[1,0,3,2] row_mask:0xf bank_mask:0xf bound_ctrl:1
	s_nop 0
	v_add_f32_dpp v28, v28, v28 quad_perm:[2,3,0,1] row_mask:0xf bank_mask:0xf bound_ctrl:1
	v_add_f32_dpp v29, v29, v29 quad_perm:[2,3,0,1] row_mask:0xf bank_mask:0xf bound_ctrl:1
	s_nop 0
	v_add_f32_dpp v28, v28, v28 row_half_mirror row_mask:0xf bank_mask:0xf bound_ctrl:1
	v_add_f32_dpp v29, v29, v29 row_half_mirror row_mask:0xf bank_mask:0xf bound_ctrl:1
	v_max_f32_e32 v27, v27, v28
	v_max_f32_e32 v26, v26, v29
	ds_bpermute_b32 v16, v11, v27
	v_max_f32_e32 v17, v27, v27
	v_max_f32_e32 v18, v26, v26
	s_waitcnt lgkmcnt(0)
	v_max_f32_e32 v16, v16, v16
	v_max_f32_e32 v16, v17, v16
	ds_bpermute_b32 v17, v11, v26
	s_waitcnt lgkmcnt(0)
	v_max_f32_e32 v17, v17, v17
	v_max_f32_e32 v17, v18, v17
	ds_bpermute_b32 v18, v13, v16
	s_waitcnt lgkmcnt(0)
	v_max_f32_e32 v18, v18, v18
	v_max_f32_e32 v16, v16, v18
	ds_bpermute_b32 v18, v13, v17
	s_waitcnt lgkmcnt(0)
	v_max_f32_e32 v18, v18, v18
	v_max_f32_e32 v17, v17, v18
	ds_bpermute_b32 v18, v20, v16
	s_waitcnt lgkmcnt(0)
	v_max_f32_e32 v18, v18, v18
	v_max_f32_e32 v16, v16, v18
	ds_bpermute_b32 v18, v20, v17
	s_waitcnt lgkmcnt(0)
	v_max_f32_e32 v18, v18, v18
	v_max_f32_e32 v17, v17, v18
	ds_bpermute_b32 v18, v21, v16
	s_waitcnt lgkmcnt(0)
	v_max_f32_e32 v18, v18, v18
	v_max_f32_e32 v16, v16, v18
	ds_bpermute_b32 v18, v21, v17
	s_waitcnt lgkmcnt(0)
	v_max_f32_e32 v18, v18, v18
	v_max_f32_e32 v17, v17, v18
	ds_bpermute_b32 v18, v22, v16
	s_waitcnt lgkmcnt(0)
	v_max_f32_e32 v18, v18, v18
	v_max_f32_e32 v16, v16, v18
	ds_bpermute_b32 v18, v22, v17
	s_waitcnt lgkmcnt(0)
	v_max_f32_e32 v18, v18, v18
	v_max_f32_e32 v18, v17, v18
	ds_bpermute_b32 v17, v23, v16
	ds_bpermute_b32 v19, v23, v18
	s_and_saveexec_b64 s[4:5], s[6:7]
	s_cbranch_execz .LBB0_2167
	s_waitcnt lgkmcnt(0)
	v_max_f32_e32 v19, v19, v19
	v_max_f32_e32 v18, v18, v18
	v_max_f32_e32 v17, v17, v17
	v_max_f32_e32 v16, v16, v16
	v_max_f32_e32 v18, v18, v19
	v_max_f32_e32 v19, v16, v17
	v_lshlrev_b32_e32 v16, 1, v25
	v_readlane_b32 s12, v246, 23
	v_ashrrev_i32_e32 v17, 31, v16
	v_readlane_b32 s13, v246, 24
	s_nop 1
	v_lshl_add_u64 v[16:17], v[16:17], 2, s[12:13]
	global_atomic_umax v[16:17], v19, off
	global_atomic_umax v[16:17], v18, off offset:4
	s_branch .LBB0_2167
